# nt (streaming) hint on the read-once f32 weight loads of the conversion and the x loads of the rows pass
# speedup vs baseline: 1.0123x; 1.0123x over previous
.LBB0_14:
	v_readlane_b32 s2, v247, 0
	v_readlane_b32 s4, v247, 1
	v_readlane_b32 s5, v247, 2
	v_readlane_b32 s42, v247, 3
	s_nop 0
	s_cmp_ge_i32 s100, s2
	s_cselect_b32 s43, 1, 0
	s_cselect_b32 s2, s2, 0
	s_sub_i32 s2, s100, s2
	v_readlane_b32 s41, v247, 9
	v_readlane_b32 s40, v247, 8
	s_nop 0
	s_cmp_lt_i32 s2, s41
	s_cselect_b32 s5, s5, s40
	s_cmpk_lt_i32 s2, 0xb00
	s_cselect_b32 s4, s4, s5
	s_add_i32 s2, s2, s4
	s_add_i32 s42, s42, s43
	s_mulk_i32 s42, 0x2680
	s_add_i32 s69, s2, s42
	s_lshl_b32 s46, s69, 7
	s_mul_hi_i32 s2, s69, 0x3531dec1
	s_lshr_b32 s4, s2, 31
	s_ashr_i32 s2, s2, 11
	s_add_i32 s42, s2, s4
	s_mul_i32 s2, s42, 0xffffd980
	s_add_i32 s70, s69, s2
	s_ashr_i32 s43, s42, 31
	s_mul_i32 s4, s42, 0x9a00000
	s_mul_hi_i32 s2, s42, 0x9a00000
	s_add_u32 s40, s3, s4
	s_addc_u32 s41, s33, s2
	s_cmpk_gt_i32 s70, 0xaff
	s_mov_b64 s[4:5], -1
	s_cbranch_scc0 .LBB0_96
	s_cmpk_gt_u32 s70, 0x15ff
	s_cbranch_scc0 .LBB0_61
	s_cmpk_gt_u32 s70, 0x197f
	s_cbranch_scc0 .LBB0_26
	s_cmpk_gt_u32 s70, 0x1eff
	s_cbranch_scc0 .LBB0_23
	s_and_b32 s44, s46, 0x780
	s_cmpk_gt_u32 s70, 0x247f
	s_cbranch_scc0 .LBB0_20
	s_lshl_b64 s[4:5], s[42:43], 24
	s_add_u32 s4, s16, s4
	s_addc_u32 s5, s17, s5
	s_add_i32 s2, s70, 0xdb80
	s_bfe_u32 s2, s2, 0xc0004
	v_lshlrev_b32_e32 v2, 2, v135
	v_lshl_or_b32 v132, s2, 19, v2
	v_lshl_add_u64 v[2:3], s[4:5], 0, v[132:133]
	s_lshl_b32 s38, s44, 2
	v_lshl_add_u64 v[2:3], v[2:3], 0, s[38:39]
	v_lshlrev_b32_e32 v132, 2, v130
	v_lshl_add_u64 v[2:3], v[2:3], 0, v[132:133]
	v_add_co_u32_e32 v4, vcc, s68, v2
	s_mov_b32 s4, 0x8000
	s_nop 0
	v_addc_co_u32_e32 v5, vcc, 0, v3, vcc
	global_load_dwordx4 v[106:109], v[2:3], off nt
	global_load_dwordx4 v[110:113], v[4:5], off nt
	v_add_co_u32_e32 v4, vcc, s4, v2
	s_mov_b32 s4, 0xa000
	s_nop 0
	v_addc_co_u32_e32 v5, vcc, 0, v3, vcc
	v_add_co_u32_e32 v6, vcc, s4, v2
	s_mov_b32 s4, 0x10000
	s_nop 0
	v_addc_co_u32_e32 v7, vcc, 0, v3, vcc
	global_load_dwordx4 v[114:117], v[4:5], off nt
	global_load_dwordx4 v[118:121], v[6:7], off nt
	v_add_co_u32_e32 v4, vcc, s4, v2
	s_mov_b32 s4, 0x12000
	s_nop 0
	v_addc_co_u32_e32 v5, vcc, 0, v3, vcc
	v_add_co_u32_e32 v6, vcc, s4, v2
	s_mov_b32 s4, 0x18000
	s_nop 0
	v_addc_co_u32_e32 v7, vcc, 0, v3, vcc
	global_load_dwordx4 v[122:125], v[4:5], off nt
	global_load_dwordx4 v[126:129], v[6:7], off nt
	v_add_co_u32_e32 v4, vcc, s4, v2
	s_mov_b32 s4, 0x1a000
	s_nop 0
	v_addc_co_u32_e32 v5, vcc, 0, v3, vcc
	v_add_co_u32_e32 v6, vcc, s4, v2
	s_mov_b32 s4, 0x20000
	s_nop 0
	v_addc_co_u32_e32 v7, vcc, 0, v3, vcc
	global_load_dwordx4 v[98:101], v[4:5], off nt
	global_load_dwordx4 v[102:105], v[6:7], off nt
	v_add_co_u32_e32 v4, vcc, s4, v2
	s_mov_b32 s4, 0x22000
	s_nop 0
	v_addc_co_u32_e32 v5, vcc, 0, v3, vcc
	v_add_co_u32_e32 v6, vcc, s4, v2
	s_mov_b32 s4, 0x28000
	s_nop 0
	v_addc_co_u32_e32 v7, vcc, 0, v3, vcc
	global_load_dwordx4 v[90:93], v[4:5], off nt
	global_load_dwordx4 v[94:97], v[6:7], off nt
	v_add_co_u32_e32 v4, vcc, s4, v2
	s_mov_b32 s4, 0x30000
	s_nop 0
	v_addc_co_u32_e32 v5, vcc, 0, v3, vcc
	v_add_co_u32_e32 v6, vcc, s58, v2
	s_lshl_b32 s2, s2, 11
	s_nop 0
	v_addc_co_u32_e32 v7, vcc, 0, v3, vcc
	global_load_dwordx4 v[82:85], v[4:5], off nt
	global_load_dwordx4 v[86:89], v[6:7], off nt
	v_add_co_u32_e32 v4, vcc, s4, v2
	s_mov_b32 s4, 0x32000
	s_nop 0
	v_addc_co_u32_e32 v5, vcc, 0, v3, vcc
	v_add_co_u32_e32 v6, vcc, s4, v2
	s_mov_b32 s4, 0x3a000
	s_nop 0
	v_addc_co_u32_e32 v7, vcc, 0, v3, vcc
	global_load_dwordx4 v[74:77], v[4:5], off nt
	global_load_dwordx4 v[78:81], v[6:7], off nt
	v_add_co_u32_e32 v4, vcc, s61, v2
	s_waitcnt vmcnt(13)
	v_bfe_u32 v132, v106, 17, 1
	v_addc_co_u32_e32 v5, vcc, 0, v3, vcc
	v_add_co_u32_e32 v6, vcc, s4, v2
	s_mov_b32 s4, 0x40000
	s_nop 0
	v_addc_co_u32_e32 v7, vcc, 0, v3, vcc
	global_load_dwordx4 v[66:69], v[4:5], off nt
	global_load_dwordx4 v[70:73], v[6:7], off nt
	v_add_co_u32_e32 v4, vcc, s4, v2
	s_mov_b32 s4, 0x42000
	s_nop 0
	v_addc_co_u32_e32 v5, vcc, 0, v3, vcc
	v_add_co_u32_e32 v6, vcc, s4, v2
	s_mov_b32 s4, 0x48000
	s_nop 0
	v_addc_co_u32_e32 v7, vcc, 0, v3, vcc
	global_load_dwordx4 v[58:61], v[4:5], off nt
	global_load_dwordx4 v[62:65], v[6:7], off nt
	v_add_co_u32_e32 v4, vcc, s4, v2
	s_mov_b32 s4, 0x4a000
	s_nop 0
	v_addc_co_u32_e32 v5, vcc, 0, v3, vcc
	v_add_co_u32_e32 v6, vcc, s4, v2
	s_mov_b32 s4, 0x50000
	s_nop 0
	v_addc_co_u32_e32 v7, vcc, 0, v3, vcc
	global_load_dwordx4 v[50:53], v[4:5], off nt
	global_load_dwordx4 v[54:57], v[6:7], off nt
	v_add_co_u32_e32 v4, vcc, s4, v2
	v_add3_u32 v106, v106, v132, s86
	s_nop 0
	v_addc_co_u32_e32 v5, vcc, 0, v3, vcc
	v_add_co_u32_e32 v6, vcc, s75, v2
	s_waitcnt vmcnt(18)
	v_bfe_u32 v132, v110, 17, 1
	v_addc_co_u32_e32 v7, vcc, 0, v3, vcc
	global_load_dwordx4 v[42:45], v[4:5], off nt
	global_load_dwordx4 v[46:49], v[6:7], off nt
	v_add_co_u32_e32 v4, vcc, s76, v2
	v_add3_u32 v110, v110, v132, s86
	s_nop 0
	v_addc_co_u32_e32 v5, vcc, 0, v3, vcc
	v_add_co_u32_e32 v6, vcc, s77, v2
	v_and_b32_e32 v106, 0xfffe0000, v106
	s_nop 0
	v_addc_co_u32_e32 v7, vcc, 0, v3, vcc
	global_load_dwordx4 v[34:37], v[4:5], off nt
	global_load_dwordx4 v[38:41], v[6:7], off nt
	v_add_co_u32_e32 v4, vcc, s78, v2
	v_and_b32_e32 v110, 0xfffe0000, v110
	s_nop 0
	v_addc_co_u32_e32 v5, vcc, 0, v3, vcc
	v_add_co_u32_e32 v6, vcc, s79, v2
	v_lshlrev_b32_e32 v132, 1, v134
	s_nop 0
	v_addc_co_u32_e32 v7, vcc, 0, v3, vcc
	global_load_dwordx4 v[26:29], v[4:5], off nt
	global_load_dwordx4 v[30:33], v[6:7], off nt
	v_add_co_u32_e32 v4, vcc, s80, v2
	s_mov_b64 s[4:5], 0x5000000
	s_nop 0
	v_addc_co_u32_e32 v5, vcc, 0, v3, vcc
	v_add_co_u32_e32 v6, vcc, s81, v2
	s_nop 1
	v_addc_co_u32_e32 v7, vcc, 0, v3, vcc
	global_load_dwordx4 v[18:21], v[4:5], off nt
	global_load_dwordx4 v[22:25], v[6:7], off nt
	v_add_co_u32_e32 v4, vcc, s82, v2
	s_nop 1
	v_addc_co_u32_e32 v5, vcc, 0, v3, vcc
	v_add_co_u32_e32 v6, vcc, s83, v2
	s_nop 1
	v_addc_co_u32_e32 v7, vcc, 0, v3, vcc
	global_load_dwordx4 v[10:13], v[4:5], off nt
	global_load_dwordx4 v[14:17], v[6:7], off nt
	v_add_co_u32_e32 v4, vcc, s84, v2
	s_nop 1
	v_addc_co_u32_e32 v5, vcc, 0, v3, vcc
	v_add_co_u32_e32 v6, vcc, s85, v2
	s_nop 1
	v_addc_co_u32_e32 v7, vcc, 0, v3, vcc
	global_load_dwordx4 v[2:5], v[4:5], off nt
	s_nop 0
	global_load_dwordx4 v[6:9], v[6:7], off nt
	v_cvt_pk_bf16_f32 v106, v106, v110
	v_add_u32_e32 v110, v142, v143
	ds_write_b32 v110, v106
	v_bfe_u32 v106, v107, 17, 1
	v_add3_u32 v106, v107, v106, s86
	v_bfe_u32 v107, v111, 17, 1
	v_and_b32_e32 v106, 0xfffe0000, v106
	v_add3_u32 v107, v111, v107, s86
	v_and_b32_e32 v107, 0xfffe0000, v107
	v_cvt_pk_bf16_f32 v106, v106, v107
	ds_write_b32 v110, v106 offset:128
	v_bfe_u32 v106, v108, 17, 1
	v_add3_u32 v106, v108, v106, s86
	v_bfe_u32 v107, v112, 17, 1
	v_and_b32_e32 v106, 0xfffe0000, v106
	v_add3_u32 v107, v112, v107, s86
	v_and_b32_e32 v107, 0xfffe0000, v107
	v_cvt_pk_bf16_f32 v106, v106, v107
	ds_write_b32 v110, v106 offset:256
	v_bfe_u32 v106, v109, 17, 1
	v_add3_u32 v106, v109, v106, s86
	v_bfe_u32 v107, v113, 17, 1
	v_and_b32_e32 v106, 0xfffe0000, v106
	v_add3_u32 v107, v113, v107, s86
	v_and_b32_e32 v107, 0xfffe0000, v107
	v_cvt_pk_bf16_f32 v106, v106, v107
	ds_write_b32 v110, v106 offset:384
	s_waitcnt vmcnt(29)
	v_bfe_u32 v106, v114, 17, 1
	v_add3_u32 v106, v114, v106, s86
	s_waitcnt vmcnt(28)
	v_bfe_u32 v107, v118, 17, 1
	v_and_b32_e32 v106, 0xfffe0000, v106
	v_add3_u32 v107, v118, v107, s86
	v_and_b32_e32 v107, 0xfffe0000, v107
	v_cvt_pk_bf16_f32 v106, v106, v107
	ds_write_b32 v110, v106 offset:1032
	v_bfe_u32 v106, v115, 17, 1
	v_add3_u32 v106, v115, v106, s86
	v_bfe_u32 v107, v119, 17, 1
	v_and_b32_e32 v106, 0xfffe0000, v106
	v_add3_u32 v107, v119, v107, s86
	v_and_b32_e32 v107, 0xfffe0000, v107
	v_cvt_pk_bf16_f32 v106, v106, v107
	ds_write_b32 v110, v106 offset:1160
	v_bfe_u32 v106, v116, 17, 1
	v_add3_u32 v106, v116, v106, s86
	v_bfe_u32 v107, v120, 17, 1
	v_and_b32_e32 v106, 0xfffe0000, v106
	v_add3_u32 v107, v120, v107, s86
	v_and_b32_e32 v107, 0xfffe0000, v107
	v_cvt_pk_bf16_f32 v106, v106, v107
	ds_write_b32 v110, v106 offset:1288
	v_bfe_u32 v106, v117, 17, 1
	v_add3_u32 v106, v117, v106, s86
	v_bfe_u32 v107, v121, 17, 1
	v_and_b32_e32 v106, 0xfffe0000, v106
	v_add3_u32 v107, v121, v107, s86
	v_and_b32_e32 v107, 0xfffe0000, v107
	v_cvt_pk_bf16_f32 v106, v106, v107
	ds_write_b32 v110, v106 offset:1416
	s_waitcnt vmcnt(27)
	v_bfe_u32 v106, v122, 17, 1
	v_add3_u32 v106, v122, v106, s86
	s_waitcnt vmcnt(26)
	v_bfe_u32 v107, v126, 17, 1
	v_and_b32_e32 v106, 0xfffe0000, v106
	v_add3_u32 v107, v126, v107, s86
	v_and_b32_e32 v107, 0xfffe0000, v107
	v_cvt_pk_bf16_f32 v106, v106, v107
	ds_write_b32 v110, v106 offset:2064
	v_bfe_u32 v106, v123, 17, 1
	v_add3_u32 v106, v123, v106, s86
	v_bfe_u32 v107, v127, 17, 1
	v_and_b32_e32 v106, 0xfffe0000, v106
	v_add3_u32 v107, v127, v107, s86
	v_and_b32_e32 v107, 0xfffe0000, v107
	v_cvt_pk_bf16_f32 v106, v106, v107
	ds_write_b32 v110, v106 offset:2192
	v_bfe_u32 v106, v124, 17, 1
	v_add3_u32 v106, v124, v106, s86
	v_bfe_u32 v107, v128, 17, 1
	v_and_b32_e32 v106, 0xfffe0000, v106
	v_add3_u32 v107, v128, v107, s86
	v_and_b32_e32 v107, 0xfffe0000, v107
	v_cvt_pk_bf16_f32 v106, v106, v107
	ds_write_b32 v110, v106 offset:2320
	v_bfe_u32 v106, v125, 17, 1
	v_add3_u32 v106, v125, v106, s86
	v_bfe_u32 v107, v129, 17, 1
	v_and_b32_e32 v106, 0xfffe0000, v106
	v_add3_u32 v107, v129, v107, s86
	v_and_b32_e32 v107, 0xfffe0000, v107
	v_cvt_pk_bf16_f32 v106, v106, v107
	ds_write_b32 v110, v106 offset:2448
	s_waitcnt vmcnt(25)
	v_bfe_u32 v106, v98, 17, 1
	v_add3_u32 v98, v98, v106, s86
	s_waitcnt vmcnt(24)
	v_bfe_u32 v106, v102, 17, 1
	v_and_b32_e32 v98, 0xfffe0000, v98
	v_add3_u32 v102, v102, v106, s86
	v_and_b32_e32 v102, 0xfffe0000, v102
	v_cvt_pk_bf16_f32 v98, v98, v102
	ds_write_b32 v110, v98 offset:3096
	v_bfe_u32 v98, v99, 17, 1
	v_add3_u32 v98, v99, v98, s86
	v_bfe_u32 v99, v103, 17, 1
	v_and_b32_e32 v98, 0xfffe0000, v98
	v_add3_u32 v99, v103, v99, s86
	v_and_b32_e32 v99, 0xfffe0000, v99
	v_cvt_pk_bf16_f32 v98, v98, v99
	ds_write_b32 v110, v98 offset:3224
	v_bfe_u32 v98, v100, 17, 1
	v_add3_u32 v98, v100, v98, s86
	v_bfe_u32 v99, v104, 17, 1
	v_and_b32_e32 v98, 0xfffe0000, v98
	v_add3_u32 v99, v104, v99, s86
	v_and_b32_e32 v99, 0xfffe0000, v99
	v_cvt_pk_bf16_f32 v98, v98, v99
	ds_write_b32 v110, v98 offset:3352
	v_bfe_u32 v98, v101, 17, 1
	v_add3_u32 v98, v101, v98, s86
	v_bfe_u32 v99, v105, 17, 1
	v_and_b32_e32 v98, 0xfffe0000, v98
	v_add3_u32 v99, v105, v99, s86
	v_and_b32_e32 v99, 0xfffe0000, v99
	v_cvt_pk_bf16_f32 v98, v98, v99
	ds_write_b32 v110, v98 offset:3480
	s_waitcnt vmcnt(23)
	v_bfe_u32 v98, v90, 17, 1
	v_add3_u32 v90, v90, v98, s86
	s_waitcnt vmcnt(22)
	v_bfe_u32 v98, v94, 17, 1
	v_and_b32_e32 v90, 0xfffe0000, v90
	v_add3_u32 v94, v94, v98, s86
	v_and_b32_e32 v94, 0xfffe0000, v94
	v_cvt_pk_bf16_f32 v90, v90, v94
	ds_write_b32 v110, v90 offset:4128
	v_bfe_u32 v90, v91, 17, 1
	v_add3_u32 v90, v91, v90, s86
	v_bfe_u32 v91, v95, 17, 1
	v_and_b32_e32 v90, 0xfffe0000, v90
	v_add3_u32 v91, v95, v91, s86
	v_and_b32_e32 v91, 0xfffe0000, v91
	v_cvt_pk_bf16_f32 v90, v90, v91
	ds_write_b32 v110, v90 offset:4256
	v_bfe_u32 v90, v92, 17, 1
	v_add3_u32 v90, v92, v90, s86
	v_bfe_u32 v91, v96, 17, 1
	v_and_b32_e32 v90, 0xfffe0000, v90
	v_add3_u32 v91, v96, v91, s86
	v_and_b32_e32 v91, 0xfffe0000, v91
	v_cvt_pk_bf16_f32 v90, v90, v91
	ds_write_b32 v110, v90 offset:4384
	v_bfe_u32 v90, v93, 17, 1
	v_add3_u32 v90, v93, v90, s86
	v_bfe_u32 v91, v97, 17, 1
	v_and_b32_e32 v90, 0xfffe0000, v90
	v_add3_u32 v91, v97, v91, s86
	v_and_b32_e32 v91, 0xfffe0000, v91
	v_cvt_pk_bf16_f32 v90, v90, v91
	ds_write_b32 v110, v90 offset:4512
	s_waitcnt vmcnt(21)
	v_bfe_u32 v90, v82, 17, 1
	v_add3_u32 v82, v82, v90, s86
	s_waitcnt vmcnt(20)
	v_bfe_u32 v90, v86, 17, 1
	v_and_b32_e32 v82, 0xfffe0000, v82
	v_add3_u32 v86, v86, v90, s86
	v_and_b32_e32 v86, 0xfffe0000, v86
	v_cvt_pk_bf16_f32 v82, v82, v86
	ds_write_b32 v110, v82 offset:5160
	v_bfe_u32 v82, v83, 17, 1
	v_add3_u32 v82, v83, v82, s86
	v_bfe_u32 v83, v87, 17, 1
	v_and_b32_e32 v82, 0xfffe0000, v82
	v_add3_u32 v83, v87, v83, s86
	v_and_b32_e32 v83, 0xfffe0000, v83
	v_cvt_pk_bf16_f32 v82, v82, v83
	ds_write_b32 v110, v82 offset:5288
	v_bfe_u32 v82, v84, 17, 1
	v_add3_u32 v82, v84, v82, s86
	v_bfe_u32 v83, v88, 17, 1
	v_and_b32_e32 v82, 0xfffe0000, v82
	v_add3_u32 v83, v88, v83, s86
	v_and_b32_e32 v83, 0xfffe0000, v83
	v_cvt_pk_bf16_f32 v82, v82, v83
	ds_write_b32 v110, v82 offset:5416
	v_bfe_u32 v82, v85, 17, 1
	v_add3_u32 v82, v85, v82, s86
	v_bfe_u32 v83, v89, 17, 1
	v_and_b32_e32 v82, 0xfffe0000, v82
	v_add3_u32 v83, v89, v83, s86
	v_and_b32_e32 v83, 0xfffe0000, v83
	v_cvt_pk_bf16_f32 v82, v82, v83
	ds_write_b32 v110, v82 offset:5544
	s_waitcnt vmcnt(19)
	v_bfe_u32 v82, v74, 17, 1
	v_add3_u32 v74, v74, v82, s86
	s_waitcnt vmcnt(18)
	v_bfe_u32 v82, v78, 17, 1
	v_and_b32_e32 v74, 0xfffe0000, v74
	v_add3_u32 v78, v78, v82, s86
	v_and_b32_e32 v78, 0xfffe0000, v78
	v_cvt_pk_bf16_f32 v74, v74, v78
	ds_write_b32 v110, v74 offset:6192
	v_bfe_u32 v74, v75, 17, 1
	v_add3_u32 v74, v75, v74, s86
	v_bfe_u32 v75, v79, 17, 1
	v_and_b32_e32 v74, 0xfffe0000, v74
	v_add3_u32 v75, v79, v75, s86
	v_and_b32_e32 v75, 0xfffe0000, v75
	v_cvt_pk_bf16_f32 v74, v74, v75
	ds_write_b32 v110, v74 offset:6320
	v_bfe_u32 v74, v76, 17, 1
	v_add3_u32 v74, v76, v74, s86
	v_bfe_u32 v75, v80, 17, 1
	v_and_b32_e32 v74, 0xfffe0000, v74
	v_add3_u32 v75, v80, v75, s86
	v_and_b32_e32 v75, 0xfffe0000, v75
	v_cvt_pk_bf16_f32 v74, v74, v75
	ds_write_b32 v110, v74 offset:6448
	v_bfe_u32 v74, v77, 17, 1
	v_add3_u32 v74, v77, v74, s86
	v_bfe_u32 v75, v81, 17, 1
	v_and_b32_e32 v74, 0xfffe0000, v74
	v_add3_u32 v75, v81, v75, s86
	v_and_b32_e32 v75, 0xfffe0000, v75
	v_cvt_pk_bf16_f32 v74, v74, v75
	ds_write_b32 v110, v74 offset:6576
	s_waitcnt vmcnt(17)
	v_bfe_u32 v74, v66, 17, 1
	v_add3_u32 v66, v66, v74, s86
	s_waitcnt vmcnt(16)
	v_bfe_u32 v74, v70, 17, 1
	v_and_b32_e32 v66, 0xfffe0000, v66
	v_add3_u32 v70, v70, v74, s86
	v_and_b32_e32 v70, 0xfffe0000, v70
	v_cvt_pk_bf16_f32 v66, v66, v70
	ds_write_b32 v110, v66 offset:7224
	v_bfe_u32 v66, v67, 17, 1
	v_add3_u32 v66, v67, v66, s86
	v_bfe_u32 v67, v71, 17, 1
	v_and_b32_e32 v66, 0xfffe0000, v66
	v_add3_u32 v67, v71, v67, s86
	v_and_b32_e32 v67, 0xfffe0000, v67
	v_cvt_pk_bf16_f32 v66, v66, v67
	ds_write_b32 v110, v66 offset:7352
	v_bfe_u32 v66, v68, 17, 1
	v_add3_u32 v66, v68, v66, s86
	v_bfe_u32 v67, v72, 17, 1
	v_and_b32_e32 v66, 0xfffe0000, v66
	v_add3_u32 v67, v72, v67, s86
	v_and_b32_e32 v67, 0xfffe0000, v67
	v_cvt_pk_bf16_f32 v66, v66, v67
	ds_write_b32 v110, v66 offset:7480
	v_bfe_u32 v66, v69, 17, 1
	v_add3_u32 v66, v69, v66, s86
	v_bfe_u32 v67, v73, 17, 1
	v_and_b32_e32 v66, 0xfffe0000, v66
	v_add3_u32 v67, v73, v67, s86
	v_and_b32_e32 v67, 0xfffe0000, v67
	v_cvt_pk_bf16_f32 v66, v66, v67
	ds_write_b32 v110, v66 offset:7608
	s_waitcnt vmcnt(15)
	v_bfe_u32 v66, v58, 17, 1
	v_add3_u32 v58, v58, v66, s86
	s_waitcnt vmcnt(14)
	v_bfe_u32 v66, v62, 17, 1
	v_and_b32_e32 v58, 0xfffe0000, v58
	v_add3_u32 v62, v62, v66, s86
	v_and_b32_e32 v62, 0xfffe0000, v62
	v_cvt_pk_bf16_f32 v58, v58, v62
	ds_write_b32 v110, v58 offset:8256
	v_bfe_u32 v58, v59, 17, 1
	v_add3_u32 v58, v59, v58, s86
	v_bfe_u32 v59, v63, 17, 1
	v_and_b32_e32 v58, 0xfffe0000, v58
	v_add3_u32 v59, v63, v59, s86
	v_and_b32_e32 v59, 0xfffe0000, v59
	v_cvt_pk_bf16_f32 v58, v58, v59
	ds_write_b32 v110, v58 offset:8384
	v_bfe_u32 v58, v60, 17, 1
	v_add3_u32 v58, v60, v58, s86
	v_bfe_u32 v59, v64, 17, 1
	v_and_b32_e32 v58, 0xfffe0000, v58
	v_add3_u32 v59, v64, v59, s86
	v_and_b32_e32 v59, 0xfffe0000, v59
	v_cvt_pk_bf16_f32 v58, v58, v59
	ds_write_b32 v110, v58 offset:8512
	v_bfe_u32 v58, v61, 17, 1
	v_add3_u32 v58, v61, v58, s86
	v_bfe_u32 v59, v65, 17, 1
	v_and_b32_e32 v58, 0xfffe0000, v58
	v_add3_u32 v59, v65, v59, s86
	v_and_b32_e32 v59, 0xfffe0000, v59
	v_cvt_pk_bf16_f32 v58, v58, v59
	ds_write_b32 v110, v58 offset:8640
	s_waitcnt vmcnt(13)
	v_bfe_u32 v58, v50, 17, 1
	v_add3_u32 v50, v50, v58, s86
	s_waitcnt vmcnt(12)
	v_bfe_u32 v58, v54, 17, 1
	v_and_b32_e32 v50, 0xfffe0000, v50
	v_add3_u32 v54, v54, v58, s86
	v_and_b32_e32 v54, 0xfffe0000, v54
	v_cvt_pk_bf16_f32 v50, v50, v54
	ds_write_b32 v110, v50 offset:9288
	v_bfe_u32 v50, v51, 17, 1
	v_add3_u32 v50, v51, v50, s86
	v_bfe_u32 v51, v55, 17, 1
	v_and_b32_e32 v50, 0xfffe0000, v50
	v_add3_u32 v51, v55, v51, s86
	v_and_b32_e32 v51, 0xfffe0000, v51
	v_cvt_pk_bf16_f32 v50, v50, v51
	ds_write_b32 v110, v50 offset:9416
	v_bfe_u32 v50, v52, 17, 1
	v_add3_u32 v50, v52, v50, s86
	v_bfe_u32 v51, v56, 17, 1
	v_and_b32_e32 v50, 0xfffe0000, v50
	v_add3_u32 v51, v56, v51, s86
	v_and_b32_e32 v51, 0xfffe0000, v51
	v_cvt_pk_bf16_f32 v50, v50, v51
	ds_write_b32 v110, v50 offset:9544
	v_bfe_u32 v50, v53, 17, 1
	v_add3_u32 v50, v53, v50, s86
	v_bfe_u32 v51, v57, 17, 1
	v_and_b32_e32 v50, 0xfffe0000, v50
	v_add3_u32 v51, v57, v51, s86
	v_and_b32_e32 v51, 0xfffe0000, v51
	v_cvt_pk_bf16_f32 v50, v50, v51
	ds_write_b32 v110, v50 offset:9672
	s_waitcnt vmcnt(11)
	v_bfe_u32 v50, v42, 17, 1
	v_add3_u32 v42, v42, v50, s86
	s_waitcnt vmcnt(10)
	v_bfe_u32 v50, v46, 17, 1
	v_and_b32_e32 v42, 0xfffe0000, v42
	v_add3_u32 v46, v46, v50, s86
	v_and_b32_e32 v46, 0xfffe0000, v46
	v_cvt_pk_bf16_f32 v42, v42, v46
	ds_write_b32 v110, v42 offset:10320
	v_bfe_u32 v42, v43, 17, 1
	v_add3_u32 v42, v43, v42, s86
	v_bfe_u32 v43, v47, 17, 1
	v_and_b32_e32 v42, 0xfffe0000, v42
	v_add3_u32 v43, v47, v43, s86
	v_and_b32_e32 v43, 0xfffe0000, v43
	v_cvt_pk_bf16_f32 v42, v42, v43
	ds_write_b32 v110, v42 offset:10448
	v_bfe_u32 v42, v44, 17, 1
	v_add3_u32 v42, v44, v42, s86
	v_bfe_u32 v43, v48, 17, 1
	v_and_b32_e32 v42, 0xfffe0000, v42
	v_add3_u32 v43, v48, v43, s86
	v_and_b32_e32 v43, 0xfffe0000, v43
	v_cvt_pk_bf16_f32 v42, v42, v43
	ds_write_b32 v110, v42 offset:10576
	v_bfe_u32 v42, v45, 17, 1
	v_add3_u32 v42, v45, v42, s86
	v_bfe_u32 v43, v49, 17, 1
	v_and_b32_e32 v42, 0xfffe0000, v42
	v_add3_u32 v43, v49, v43, s86
	v_and_b32_e32 v43, 0xfffe0000, v43
	v_cvt_pk_bf16_f32 v42, v42, v43
	ds_write_b32 v110, v42 offset:10704
	s_waitcnt vmcnt(9)
	v_bfe_u32 v42, v34, 17, 1
	v_add3_u32 v34, v34, v42, s86
	s_waitcnt vmcnt(8)
	v_bfe_u32 v42, v38, 17, 1
	v_and_b32_e32 v34, 0xfffe0000, v34
	v_add3_u32 v38, v38, v42, s86
	v_and_b32_e32 v38, 0xfffe0000, v38
	v_cvt_pk_bf16_f32 v34, v34, v38
	ds_write_b32 v110, v34 offset:11352
	v_bfe_u32 v34, v35, 17, 1
	v_add3_u32 v34, v35, v34, s86
	v_bfe_u32 v35, v39, 17, 1
	v_and_b32_e32 v34, 0xfffe0000, v34
	v_add3_u32 v35, v39, v35, s86
	v_and_b32_e32 v35, 0xfffe0000, v35
	v_cvt_pk_bf16_f32 v34, v34, v35
	ds_write_b32 v110, v34 offset:11480
	v_bfe_u32 v34, v36, 17, 1
	v_add3_u32 v34, v36, v34, s86
	v_bfe_u32 v35, v40, 17, 1
	v_and_b32_e32 v34, 0xfffe0000, v34
	v_add3_u32 v35, v40, v35, s86
	v_and_b32_e32 v35, 0xfffe0000, v35
	v_cvt_pk_bf16_f32 v34, v34, v35
	ds_write_b32 v110, v34 offset:11608
	v_bfe_u32 v34, v37, 17, 1
	v_add3_u32 v34, v37, v34, s86
	v_bfe_u32 v35, v41, 17, 1
	v_and_b32_e32 v34, 0xfffe0000, v34
	v_add3_u32 v35, v41, v35, s86
	v_and_b32_e32 v35, 0xfffe0000, v35
	v_cvt_pk_bf16_f32 v34, v34, v35
	ds_write_b32 v110, v34 offset:11736
	s_waitcnt vmcnt(7)
	v_bfe_u32 v34, v26, 17, 1
	v_add3_u32 v26, v26, v34, s86
	s_waitcnt vmcnt(6)
	v_bfe_u32 v34, v30, 17, 1
	v_and_b32_e32 v26, 0xfffe0000, v26
	v_add3_u32 v30, v30, v34, s86
	v_and_b32_e32 v30, 0xfffe0000, v30
	v_cvt_pk_bf16_f32 v26, v26, v30
	ds_write_b32 v110, v26 offset:12384
	v_bfe_u32 v26, v27, 17, 1
	v_add3_u32 v26, v27, v26, s86
	v_bfe_u32 v27, v31, 17, 1
	v_and_b32_e32 v26, 0xfffe0000, v26
	v_add3_u32 v27, v31, v27, s86
	v_and_b32_e32 v27, 0xfffe0000, v27
	v_cvt_pk_bf16_f32 v26, v26, v27
	ds_write_b32 v110, v26 offset:12512
	v_bfe_u32 v26, v28, 17, 1
	v_add3_u32 v26, v28, v26, s86
	v_bfe_u32 v27, v32, 17, 1
	v_and_b32_e32 v26, 0xfffe0000, v26
	v_add3_u32 v27, v32, v27, s86
	v_and_b32_e32 v27, 0xfffe0000, v27
	v_cvt_pk_bf16_f32 v26, v26, v27
	ds_write_b32 v110, v26 offset:12640
	v_bfe_u32 v26, v29, 17, 1
	v_add3_u32 v26, v29, v26, s86
	v_bfe_u32 v27, v33, 17, 1
	v_and_b32_e32 v26, 0xfffe0000, v26
	v_add3_u32 v27, v33, v27, s86
	v_and_b32_e32 v27, 0xfffe0000, v27
	v_cvt_pk_bf16_f32 v26, v26, v27
	ds_write_b32 v110, v26 offset:12768
	s_waitcnt vmcnt(5)
	v_bfe_u32 v26, v18, 17, 1
	v_add3_u32 v18, v18, v26, s86
	s_waitcnt vmcnt(4)
	v_bfe_u32 v26, v22, 17, 1
	v_and_b32_e32 v18, 0xfffe0000, v18
	v_add3_u32 v22, v22, v26, s86
	v_and_b32_e32 v22, 0xfffe0000, v22
	v_cvt_pk_bf16_f32 v18, v18, v22
	ds_write_b32 v110, v18 offset:13416
	v_bfe_u32 v18, v19, 17, 1
	v_add3_u32 v18, v19, v18, s86
	v_bfe_u32 v19, v23, 17, 1
	v_and_b32_e32 v18, 0xfffe0000, v18
	v_add3_u32 v19, v23, v19, s86
	v_and_b32_e32 v19, 0xfffe0000, v19
	v_cvt_pk_bf16_f32 v18, v18, v19
	ds_write_b32 v110, v18 offset:13544
	v_bfe_u32 v18, v20, 17, 1
	v_add3_u32 v18, v20, v18, s86
	v_bfe_u32 v19, v24, 17, 1
	v_and_b32_e32 v18, 0xfffe0000, v18
	v_add3_u32 v19, v24, v19, s86
	v_and_b32_e32 v19, 0xfffe0000, v19
	v_cvt_pk_bf16_f32 v18, v18, v19
	ds_write_b32 v110, v18 offset:13672
	v_bfe_u32 v18, v21, 17, 1
	v_add3_u32 v18, v21, v18, s86
	v_bfe_u32 v19, v25, 17, 1
	v_and_b32_e32 v18, 0xfffe0000, v18
	v_add3_u32 v19, v25, v19, s86
	v_and_b32_e32 v19, 0xfffe0000, v19
	v_cvt_pk_bf16_f32 v18, v18, v19
	ds_write_b32 v110, v18 offset:13800
	s_waitcnt vmcnt(3)
	v_bfe_u32 v18, v10, 17, 1
	v_add3_u32 v10, v10, v18, s86
	s_waitcnt vmcnt(2)
	v_bfe_u32 v18, v14, 17, 1
	v_and_b32_e32 v10, 0xfffe0000, v10
	v_add3_u32 v14, v14, v18, s86
	v_and_b32_e32 v14, 0xfffe0000, v14
	v_cvt_pk_bf16_f32 v10, v10, v14
	ds_write_b32 v110, v10 offset:14448
	v_bfe_u32 v10, v11, 17, 1
	v_add3_u32 v10, v11, v10, s86
	v_bfe_u32 v11, v15, 17, 1
	v_and_b32_e32 v10, 0xfffe0000, v10
	v_add3_u32 v11, v15, v11, s86
	v_and_b32_e32 v11, 0xfffe0000, v11
	v_cvt_pk_bf16_f32 v10, v10, v11
	ds_write_b32 v110, v10 offset:14576
	v_bfe_u32 v10, v12, 17, 1
	v_add3_u32 v10, v12, v10, s86
	v_bfe_u32 v11, v16, 17, 1
	v_and_b32_e32 v10, 0xfffe0000, v10
	v_add3_u32 v11, v16, v11, s86
	v_and_b32_e32 v11, 0xfffe0000, v11
	v_cvt_pk_bf16_f32 v10, v10, v11
	ds_write_b32 v110, v10 offset:14704
	v_bfe_u32 v10, v13, 17, 1
	v_add3_u32 v10, v13, v10, s86
	v_bfe_u32 v11, v17, 17, 1
	v_and_b32_e32 v10, 0xfffe0000, v10
	v_add3_u32 v11, v17, v11, s86
	v_and_b32_e32 v11, 0xfffe0000, v11
	v_cvt_pk_bf16_f32 v10, v10, v11
	ds_write_b32 v110, v10 offset:14832
	s_waitcnt vmcnt(1)
	v_bfe_u32 v10, v2, 17, 1
	v_add3_u32 v2, v2, v10, s86
	s_waitcnt vmcnt(0)
	v_bfe_u32 v10, v6, 17, 1
	v_and_b32_e32 v2, 0xfffe0000, v2
	v_add3_u32 v6, v6, v10, s86
	v_and_b32_e32 v6, 0xfffe0000, v6
	v_cvt_pk_bf16_f32 v2, v2, v6
	ds_write_b32 v110, v2 offset:15480
	v_bfe_u32 v2, v3, 17, 1
	v_add3_u32 v2, v3, v2, s86
	v_bfe_u32 v3, v7, 17, 1
	v_and_b32_e32 v2, 0xfffe0000, v2
	v_add3_u32 v3, v7, v3, s86
	v_and_b32_e32 v3, 0xfffe0000, v3
	v_cvt_pk_bf16_f32 v2, v2, v3
	ds_write_b32 v110, v2 offset:15608
	v_bfe_u32 v2, v4, 17, 1
	v_add3_u32 v2, v4, v2, s86
	v_bfe_u32 v3, v8, 17, 1
	v_and_b32_e32 v2, 0xfffe0000, v2
	v_add3_u32 v3, v8, v3, s86
	v_and_b32_e32 v3, 0xfffe0000, v3
	v_cvt_pk_bf16_f32 v2, v2, v3
	ds_write_b32 v110, v2 offset:15736
	v_bfe_u32 v2, v5, 17, 1
	v_add3_u32 v2, v5, v2, s86
	v_bfe_u32 v3, v9, 17, 1
	v_and_b32_e32 v2, 0xfffe0000, v2
	v_add3_u32 v3, v9, v3, s86
	v_and_b32_e32 v3, 0xfffe0000, v3
	v_cvt_pk_bf16_f32 v2, v2, v3
	ds_write_b32 v110, v2 offset:15864
	s_waitcnt lgkmcnt(0)
	ds_read2_b32 v[20:21], v146 offset1:8
	ds_read2_b32 v[4:5], v146 offset0:129 offset1:137
	v_add_u32_e32 v30, 0x400, v146
	ds_read2_b32 v[22:23], v30 offset0:2 offset1:10
	ds_read2_b32 v[6:7], v30 offset0:131 offset1:139
	v_add_u32_e32 v32, 0x400, v147
	ds_read2_b32 v[24:25], v147 offset1:8
	ds_read2_b32 v[12:13], v147 offset0:129 offset1:137
	ds_read2_b32 v[26:27], v32 offset0:2 offset1:10
	ds_read2_b32 v[14:15], v32 offset0:131 offset1:139
	v_or_b32_e32 v31, s44, v131
	v_lshl_add_u64 v[2:3], s[40:41], 0, v[132:133]
	s_waitcnt lgkmcnt(6)
	v_mov_b32_e32 v9, v4
	v_or3_b32 v4, v31, v145, s2
	v_or_b32_e32 v33, s44, v144
	v_lshl_add_u64 v[2:3], v[2:3], 0, s[4:5]
	v_lshlrev_b32_e32 v132, 7, v4
	v_or3_b32 v4, v33, v145, s2
	v_mov_b32_e32 v8, v20
	s_waitcnt lgkmcnt(5)
	v_mov_b32_e32 v10, v22
	s_waitcnt lgkmcnt(4)
	v_mov_b32_e32 v11, v6
	v_lshl_add_u64 v[16:17], v[2:3], 0, v[132:133]
	v_lshlrev_b32_e32 v132, 7, v4
	global_store_dwordx4 v[16:17], v[8:11], off
	v_lshl_add_u64 v[16:17], v[2:3], 0, v[132:133]
	v_add_u32_e32 v4, 0x400, v149
	s_waitcnt lgkmcnt(3)
	v_mov_b32_e32 v8, v24
	s_waitcnt lgkmcnt(2)
	v_mov_b32_e32 v9, v12
	s_waitcnt lgkmcnt(1)
	v_mov_b32_e32 v10, v26
	s_waitcnt lgkmcnt(0)
	v_mov_b32_e32 v11, v14
	global_store_dwordx4 v[16:17], v[8:11], off
	ds_read2_b32 v[10:11], v4 offset0:2 offset1:131
	v_or3_b32 v4, v31, v148, s2
	ds_read2_b32 v[8:9], v149 offset1:129
	v_lshlrev_b32_e32 v132, 7, v4
	v_add_u32_e32 v4, 0x400, v150
	ds_read2_b32 v[16:17], v150 offset1:129
	ds_read2_b32 v[18:19], v4 offset0:2 offset1:131
	v_or3_b32 v4, v33, v148, s2
	v_lshl_add_u64 v[28:29], v[2:3], 0, v[132:133]
	v_lshlrev_b32_e32 v132, 7, v4
	s_waitcnt lgkmcnt(2)
	global_store_dwordx4 v[28:29], v[8:11], off
	v_mov_b32_e32 v4, v21
	v_mov_b32_e32 v6, v23
	v_lshl_add_u64 v[8:9], v[2:3], 0, v[132:133]
	s_waitcnt lgkmcnt(0)
	global_store_dwordx4 v[8:9], v[16:19], off
	v_or3_b32 v8, v31, v151, s2
	v_lshlrev_b32_e32 v132, 7, v8
	v_lshl_add_u64 v[8:9], v[2:3], 0, v[132:133]
	global_store_dwordx4 v[8:9], v[4:7], off
	v_mov_b32_e32 v12, v25
	v_mov_b32_e32 v14, v27
	v_or3_b32 v4, v33, v151, s2
	v_add_u32_e32 v6, 0x400, v153
	v_lshlrev_b32_e32 v132, 7, v4
	ds_read2_b32 v[4:5], v153 offset1:129
	ds_read2_b32 v[6:7], v6 offset0:2 offset1:131
	v_lshl_add_u64 v[8:9], v[2:3], 0, v[132:133]
	global_store_dwordx4 v[8:9], v[12:15], off
	v_or3_b32 v8, v31, v152, s2
	v_lshlrev_b32_e32 v132, 7, v8
	v_lshl_add_u64 v[8:9], v[2:3], 0, v[132:133]
	s_waitcnt lgkmcnt(0)
	global_store_dwordx4 v[8:9], v[4:7], off
	ds_read2_b32 v[4:5], v154 offset1:129
	v_or3_b32 v8, v33, v152, s2
	v_add_u32_e32 v6, 0x400, v154
	ds_read2_b32 v[6:7], v6 offset0:2 offset1:131
	v_lshlrev_b32_e32 v132, 7, v8
	v_lshl_add_u64 v[12:13], v[2:3], 0, v[132:133]
	ds_read2_b32 v[20:21], v146 offset0:16 offset1:24
	ds_read2_b32 v[8:9], v146 offset0:145 offset1:153
	ds_read2_b32 v[22:23], v30 offset0:18 offset1:26
	ds_read2_b32 v[10:11], v30 offset0:147 offset1:155
	s_mov_b64 s[4:5], 0
	s_waitcnt lgkmcnt(4)
	global_store_dwordx4 v[12:13], v[4:7], off
	ds_read2_b32 v[24:25], v147 offset0:16 offset1:24
	ds_read2_b32 v[12:13], v147 offset0:145 offset1:153
	ds_read2_b32 v[26:27], v32 offset0:18 offset1:26
	ds_read2_b32 v[14:15], v32 offset0:147 offset1:155
	s_waitcnt lgkmcnt(6)
	v_mov_b32_e32 v5, v8
	v_or3_b32 v8, v31, v155, s2
	v_lshlrev_b32_e32 v132, 7, v8
	v_or3_b32 v8, v33, v155, s2
	v_mov_b32_e32 v4, v20
	s_waitcnt lgkmcnt(5)
	v_mov_b32_e32 v6, v22
	s_waitcnt lgkmcnt(4)
	v_mov_b32_e32 v7, v10
	v_lshl_add_u64 v[16:17], v[2:3], 0, v[132:133]
	v_lshlrev_b32_e32 v132, 7, v8
	global_store_dwordx4 v[16:17], v[4:7], off
	v_lshl_add_u64 v[16:17], v[2:3], 0, v[132:133]
	v_or3_b32 v8, v31, v158, s2
	s_waitcnt lgkmcnt(3)
	v_mov_b32_e32 v4, v24
	s_waitcnt lgkmcnt(2)
	v_mov_b32_e32 v5, v12
	s_waitcnt lgkmcnt(1)
	v_mov_b32_e32 v6, v26
	s_waitcnt lgkmcnt(0)
	v_mov_b32_e32 v7, v14
	global_store_dwordx4 v[16:17], v[4:7], off
	ds_read2_b32 v[4:5], v159 offset1:129
	v_lshlrev_b32_e32 v132, 7, v8
	v_add_u32_e32 v6, 0x400, v159
	ds_read2_b32 v[6:7], v6 offset0:2 offset1:131
	v_add_u32_e32 v8, 0x400, v160
	ds_read2_b32 v[16:17], v160 offset1:129
	ds_read2_b32 v[18:19], v8 offset0:2 offset1:131
	v_lshl_add_u64 v[28:29], v[2:3], 0, v[132:133]
	s_waitcnt lgkmcnt(2)
	global_store_dwordx4 v[28:29], v[4:7], off
	v_mov_b32_e32 v8, v21
	v_mov_b32_e32 v10, v23
	v_or3_b32 v4, v33, v158, s2
	v_lshlrev_b32_e32 v132, 7, v4
	v_lshl_add_u64 v[4:5], v[2:3], 0, v[132:133]
	s_waitcnt lgkmcnt(0)
	global_store_dwordx4 v[4:5], v[16:19], off
	v_or3_b32 v4, v31, v161, s2
	v_lshlrev_b32_e32 v132, 7, v4
	v_lshl_add_u64 v[4:5], v[2:3], 0, v[132:133]
	global_store_dwordx4 v[4:5], v[8:11], off
	v_or3_b32 v4, v33, v161, s2
	v_lshlrev_b32_e32 v132, 7, v4
	v_mov_b32_e32 v12, v25
	v_mov_b32_e32 v14, v27
	v_lshl_add_u64 v[4:5], v[2:3], 0, v[132:133]
	v_add_u32_e32 v6, 0x400, v163
	global_store_dwordx4 v[4:5], v[12:15], off
	ds_read2_b32 v[4:5], v163 offset1:129
	ds_read2_b32 v[6:7], v6 offset0:2 offset1:131
	v_or3_b32 v8, v31, v162, s2
	v_add_u32_e32 v10, 0x400, v164
	v_lshlrev_b32_e32 v132, 7, v8
	ds_read2_b32 v[8:9], v164 offset1:129
	ds_read2_b32 v[10:11], v10 offset0:2 offset1:131
	v_lshl_add_u64 v[12:13], v[2:3], 0, v[132:133]
	s_waitcnt lgkmcnt(2)
	global_store_dwordx4 v[12:13], v[4:7], off
	s_nop 1
	v_or3_b32 v4, v33, v162, s2
	v_lshlrev_b32_e32 v132, 7, v4
	v_lshl_add_u64 v[2:3], v[2:3], 0, v[132:133]
	s_waitcnt lgkmcnt(0)
	global_store_dwordx4 v[2:3], v[8:11], off
	s_waitcnt lgkmcnt(0)
.LBB0_20:
	s_andn2_b64 vcc, exec, s[4:5]
	s_cbranch_vccnz .LBB0_22
	s_mul_i32 s4, s42, 0x2c00000
	s_mul_hi_i32 s2, s42, 0x2c00000
	s_add_u32 s4, s22, s4
	s_addc_u32 s5, s23, s2
	s_add_i32 s2, s70, 0xe100
	s_bfe_u32 s2, s2, 0xc0004
	v_lshlrev_b32_e32 v2, 2, v135
	v_lshl_or_b32 v132, s2, 19, v2
	v_lshl_add_u64 v[2:3], s[4:5], 0, v[132:133]
	s_lshl_b32 s38, s44, 2
	v_lshl_add_u64 v[2:3], v[2:3], 0, s[38:39]
	v_lshlrev_b32_e32 v132, 2, v130
	v_lshl_add_u64 v[2:3], v[2:3], 0, v[132:133]
	v_add_co_u32_e32 v4, vcc, s68, v2
	s_mov_b32 s4, 0x8000
	s_nop 0
	v_addc_co_u32_e32 v5, vcc, 0, v3, vcc
	global_load_dwordx4 v[106:109], v[2:3], off nt
	global_load_dwordx4 v[110:113], v[4:5], off nt
	v_add_co_u32_e32 v4, vcc, s4, v2
	s_mov_b32 s4, 0xa000
	s_nop 0
	v_addc_co_u32_e32 v5, vcc, 0, v3, vcc
	v_add_co_u32_e32 v6, vcc, s4, v2
	s_mov_b32 s4, 0x10000
	s_nop 0
	v_addc_co_u32_e32 v7, vcc, 0, v3, vcc
	global_load_dwordx4 v[114:117], v[4:5], off nt
	global_load_dwordx4 v[118:121], v[6:7], off nt
	v_add_co_u32_e32 v4, vcc, s4, v2
	s_mov_b32 s4, 0x12000
	s_nop 0
	v_addc_co_u32_e32 v5, vcc, 0, v3, vcc
	v_add_co_u32_e32 v6, vcc, s4, v2
	s_mov_b32 s4, 0x18000
	s_nop 0
	v_addc_co_u32_e32 v7, vcc, 0, v3, vcc
	global_load_dwordx4 v[122:125], v[4:5], off nt
	global_load_dwordx4 v[126:129], v[6:7], off nt
	v_add_co_u32_e32 v4, vcc, s4, v2
	s_mov_b32 s4, 0x1a000
	s_nop 0
	v_addc_co_u32_e32 v5, vcc, 0, v3, vcc
	v_add_co_u32_e32 v6, vcc, s4, v2
	s_mov_b32 s4, 0x20000
	s_nop 0
	v_addc_co_u32_e32 v7, vcc, 0, v3, vcc
	global_load_dwordx4 v[98:101], v[4:5], off nt
	global_load_dwordx4 v[102:105], v[6:7], off nt
	v_add_co_u32_e32 v4, vcc, s4, v2
	s_mov_b32 s4, 0x22000
	s_nop 0
	v_addc_co_u32_e32 v5, vcc, 0, v3, vcc
	v_add_co_u32_e32 v6, vcc, s4, v2
	s_mov_b32 s4, 0x28000
	s_nop 0
	v_addc_co_u32_e32 v7, vcc, 0, v3, vcc
	global_load_dwordx4 v[90:93], v[4:5], off nt
	global_load_dwordx4 v[94:97], v[6:7], off nt
	v_add_co_u32_e32 v4, vcc, s4, v2
	s_mov_b32 s4, 0x30000
	s_nop 0
	v_addc_co_u32_e32 v5, vcc, 0, v3, vcc
	v_add_co_u32_e32 v6, vcc, s58, v2
	s_lshl_b32 s2, s2, 11
	s_nop 0
	v_addc_co_u32_e32 v7, vcc, 0, v3, vcc
	global_load_dwordx4 v[82:85], v[4:5], off nt
	global_load_dwordx4 v[86:89], v[6:7], off nt
	v_add_co_u32_e32 v4, vcc, s4, v2
	s_mov_b32 s4, 0x32000
	s_nop 0
	v_addc_co_u32_e32 v5, vcc, 0, v3, vcc
	v_add_co_u32_e32 v6, vcc, s4, v2
	s_mov_b32 s4, 0x3a000
	s_nop 0
	v_addc_co_u32_e32 v7, vcc, 0, v3, vcc
	global_load_dwordx4 v[74:77], v[4:5], off nt
	global_load_dwordx4 v[78:81], v[6:7], off nt
	v_add_co_u32_e32 v4, vcc, s61, v2
	s_waitcnt vmcnt(13)
	v_bfe_u32 v132, v106, 17, 1
	v_addc_co_u32_e32 v5, vcc, 0, v3, vcc
	v_add_co_u32_e32 v6, vcc, s4, v2
	s_mov_b32 s4, 0x40000
	s_nop 0
	v_addc_co_u32_e32 v7, vcc, 0, v3, vcc
	global_load_dwordx4 v[66:69], v[4:5], off nt
	global_load_dwordx4 v[70:73], v[6:7], off nt
	v_add_co_u32_e32 v4, vcc, s4, v2
	s_mov_b32 s4, 0x42000
	s_nop 0
	v_addc_co_u32_e32 v5, vcc, 0, v3, vcc
	v_add_co_u32_e32 v6, vcc, s4, v2
	s_mov_b32 s4, 0x48000
	s_nop 0
	v_addc_co_u32_e32 v7, vcc, 0, v3, vcc
	global_load_dwordx4 v[58:61], v[4:5], off nt
	global_load_dwordx4 v[62:65], v[6:7], off nt
	v_add_co_u32_e32 v4, vcc, s4, v2
	s_mov_b32 s4, 0x4a000
	s_nop 0
	v_addc_co_u32_e32 v5, vcc, 0, v3, vcc
	v_add_co_u32_e32 v6, vcc, s4, v2
	s_mov_b32 s4, 0x50000
	s_nop 0
	v_addc_co_u32_e32 v7, vcc, 0, v3, vcc
	global_load_dwordx4 v[50:53], v[4:5], off nt
	global_load_dwordx4 v[54:57], v[6:7], off nt
	v_add_co_u32_e32 v4, vcc, s4, v2
	v_add3_u32 v106, v106, v132, s86
	s_nop 0
	v_addc_co_u32_e32 v5, vcc, 0, v3, vcc
	v_add_co_u32_e32 v6, vcc, s75, v2
	s_waitcnt vmcnt(18)
	v_bfe_u32 v132, v110, 17, 1
	v_addc_co_u32_e32 v7, vcc, 0, v3, vcc
	global_load_dwordx4 v[42:45], v[4:5], off nt
	global_load_dwordx4 v[46:49], v[6:7], off nt
	v_add_co_u32_e32 v4, vcc, s76, v2
	v_add3_u32 v110, v110, v132, s86
	s_nop 0
	v_addc_co_u32_e32 v5, vcc, 0, v3, vcc
	v_add_co_u32_e32 v6, vcc, s77, v2
	v_and_b32_e32 v106, 0xfffe0000, v106
	s_nop 0
	v_addc_co_u32_e32 v7, vcc, 0, v3, vcc
	global_load_dwordx4 v[34:37], v[4:5], off nt
	global_load_dwordx4 v[38:41], v[6:7], off nt
	v_add_co_u32_e32 v4, vcc, s78, v2
	v_and_b32_e32 v110, 0xfffe0000, v110
	s_nop 0
	v_addc_co_u32_e32 v5, vcc, 0, v3, vcc
	v_add_co_u32_e32 v6, vcc, s79, v2
	v_lshlrev_b32_e32 v132, 1, v134
	s_nop 0
	v_addc_co_u32_e32 v7, vcc, 0, v3, vcc
	global_load_dwordx4 v[26:29], v[4:5], off nt
	global_load_dwordx4 v[30:33], v[6:7], off nt
	v_add_co_u32_e32 v4, vcc, s80, v2
	s_mov_b64 s[4:5], 0x8400000
	s_nop 0
	v_addc_co_u32_e32 v5, vcc, 0, v3, vcc
	v_add_co_u32_e32 v6, vcc, s81, v2
	s_nop 1
	v_addc_co_u32_e32 v7, vcc, 0, v3, vcc
	global_load_dwordx4 v[18:21], v[4:5], off nt
	global_load_dwordx4 v[22:25], v[6:7], off nt
	v_add_co_u32_e32 v4, vcc, s82, v2
	s_nop 1
	v_addc_co_u32_e32 v5, vcc, 0, v3, vcc
	v_add_co_u32_e32 v6, vcc, s83, v2
	s_nop 1
	v_addc_co_u32_e32 v7, vcc, 0, v3, vcc
	global_load_dwordx4 v[10:13], v[4:5], off nt
	global_load_dwordx4 v[14:17], v[6:7], off nt
	v_add_co_u32_e32 v4, vcc, s84, v2
	s_nop 1
	v_addc_co_u32_e32 v5, vcc, 0, v3, vcc
	v_add_co_u32_e32 v6, vcc, s85, v2
	s_nop 1
	v_addc_co_u32_e32 v7, vcc, 0, v3, vcc
	global_load_dwordx4 v[2:5], v[4:5], off nt
	s_nop 0
	global_load_dwordx4 v[6:9], v[6:7], off nt
	v_cvt_pk_bf16_f32 v106, v106, v110
	v_add_u32_e32 v110, v142, v143
	ds_write_b32 v110, v106
	v_bfe_u32 v106, v107, 17, 1
	v_add3_u32 v106, v107, v106, s86
	v_bfe_u32 v107, v111, 17, 1
	v_and_b32_e32 v106, 0xfffe0000, v106
	v_add3_u32 v107, v111, v107, s86
	v_and_b32_e32 v107, 0xfffe0000, v107
	v_cvt_pk_bf16_f32 v106, v106, v107
	ds_write_b32 v110, v106 offset:128
	v_bfe_u32 v106, v108, 17, 1
	v_add3_u32 v106, v108, v106, s86
	v_bfe_u32 v107, v112, 17, 1
	v_and_b32_e32 v106, 0xfffe0000, v106
	v_add3_u32 v107, v112, v107, s86
	v_and_b32_e32 v107, 0xfffe0000, v107
	v_cvt_pk_bf16_f32 v106, v106, v107
	ds_write_b32 v110, v106 offset:256
	v_bfe_u32 v106, v109, 17, 1
	v_add3_u32 v106, v109, v106, s86
	v_bfe_u32 v107, v113, 17, 1
	v_and_b32_e32 v106, 0xfffe0000, v106
	v_add3_u32 v107, v113, v107, s86
	v_and_b32_e32 v107, 0xfffe0000, v107
	v_cvt_pk_bf16_f32 v106, v106, v107
	ds_write_b32 v110, v106 offset:384
	s_waitcnt vmcnt(29)
	v_bfe_u32 v106, v114, 17, 1
	v_add3_u32 v106, v114, v106, s86
	s_waitcnt vmcnt(28)
	v_bfe_u32 v107, v118, 17, 1
	v_and_b32_e32 v106, 0xfffe0000, v106
	v_add3_u32 v107, v118, v107, s86
	v_and_b32_e32 v107, 0xfffe0000, v107
	v_cvt_pk_bf16_f32 v106, v106, v107
	ds_write_b32 v110, v106 offset:1032
	v_bfe_u32 v106, v115, 17, 1
	v_add3_u32 v106, v115, v106, s86
	v_bfe_u32 v107, v119, 17, 1
	v_and_b32_e32 v106, 0xfffe0000, v106
	v_add3_u32 v107, v119, v107, s86
	v_and_b32_e32 v107, 0xfffe0000, v107
	v_cvt_pk_bf16_f32 v106, v106, v107
	ds_write_b32 v110, v106 offset:1160
	v_bfe_u32 v106, v116, 17, 1
	v_add3_u32 v106, v116, v106, s86
	v_bfe_u32 v107, v120, 17, 1
	v_and_b32_e32 v106, 0xfffe0000, v106
	v_add3_u32 v107, v120, v107, s86
	v_and_b32_e32 v107, 0xfffe0000, v107
	v_cvt_pk_bf16_f32 v106, v106, v107
	ds_write_b32 v110, v106 offset:1288
	v_bfe_u32 v106, v117, 17, 1
	v_add3_u32 v106, v117, v106, s86
	v_bfe_u32 v107, v121, 17, 1
	v_and_b32_e32 v106, 0xfffe0000, v106
	v_add3_u32 v107, v121, v107, s86
	v_and_b32_e32 v107, 0xfffe0000, v107
	v_cvt_pk_bf16_f32 v106, v106, v107
	ds_write_b32 v110, v106 offset:1416
	s_waitcnt vmcnt(27)
	v_bfe_u32 v106, v122, 17, 1
	v_add3_u32 v106, v122, v106, s86
	s_waitcnt vmcnt(26)
	v_bfe_u32 v107, v126, 17, 1
	v_and_b32_e32 v106, 0xfffe0000, v106
	v_add3_u32 v107, v126, v107, s86
	v_and_b32_e32 v107, 0xfffe0000, v107
	v_cvt_pk_bf16_f32 v106, v106, v107
	ds_write_b32 v110, v106 offset:2064
	v_bfe_u32 v106, v123, 17, 1
	v_add3_u32 v106, v123, v106, s86
	v_bfe_u32 v107, v127, 17, 1
	v_and_b32_e32 v106, 0xfffe0000, v106
	v_add3_u32 v107, v127, v107, s86
	v_and_b32_e32 v107, 0xfffe0000, v107
	v_cvt_pk_bf16_f32 v106, v106, v107
	ds_write_b32 v110, v106 offset:2192
	v_bfe_u32 v106, v124, 17, 1
	v_add3_u32 v106, v124, v106, s86
	v_bfe_u32 v107, v128, 17, 1
	v_and_b32_e32 v106, 0xfffe0000, v106
	v_add3_u32 v107, v128, v107, s86
	v_and_b32_e32 v107, 0xfffe0000, v107
	v_cvt_pk_bf16_f32 v106, v106, v107
	ds_write_b32 v110, v106 offset:2320
	v_bfe_u32 v106, v125, 17, 1
	v_add3_u32 v106, v125, v106, s86
	v_bfe_u32 v107, v129, 17, 1
	v_and_b32_e32 v106, 0xfffe0000, v106
	v_add3_u32 v107, v129, v107, s86
	v_and_b32_e32 v107, 0xfffe0000, v107
	v_cvt_pk_bf16_f32 v106, v106, v107
	ds_write_b32 v110, v106 offset:2448
	s_waitcnt vmcnt(25)
	v_bfe_u32 v106, v98, 17, 1
	v_add3_u32 v98, v98, v106, s86
	s_waitcnt vmcnt(24)
	v_bfe_u32 v106, v102, 17, 1
	v_and_b32_e32 v98, 0xfffe0000, v98
	v_add3_u32 v102, v102, v106, s86
	v_and_b32_e32 v102, 0xfffe0000, v102
	v_cvt_pk_bf16_f32 v98, v98, v102
	ds_write_b32 v110, v98 offset:3096
	v_bfe_u32 v98, v99, 17, 1
	v_add3_u32 v98, v99, v98, s86
	v_bfe_u32 v99, v103, 17, 1
	v_and_b32_e32 v98, 0xfffe0000, v98
	v_add3_u32 v99, v103, v99, s86
	v_and_b32_e32 v99, 0xfffe0000, v99
	v_cvt_pk_bf16_f32 v98, v98, v99
	ds_write_b32 v110, v98 offset:3224
	v_bfe_u32 v98, v100, 17, 1
	v_add3_u32 v98, v100, v98, s86
	v_bfe_u32 v99, v104, 17, 1
	v_and_b32_e32 v98, 0xfffe0000, v98
	v_add3_u32 v99, v104, v99, s86
	v_and_b32_e32 v99, 0xfffe0000, v99
	v_cvt_pk_bf16_f32 v98, v98, v99
	ds_write_b32 v110, v98 offset:3352
	v_bfe_u32 v98, v101, 17, 1
	v_add3_u32 v98, v101, v98, s86
	v_bfe_u32 v99, v105, 17, 1
	v_and_b32_e32 v98, 0xfffe0000, v98
	v_add3_u32 v99, v105, v99, s86
	v_and_b32_e32 v99, 0xfffe0000, v99
	v_cvt_pk_bf16_f32 v98, v98, v99
	ds_write_b32 v110, v98 offset:3480
	s_waitcnt vmcnt(23)
	v_bfe_u32 v98, v90, 17, 1
	v_add3_u32 v90, v90, v98, s86
	s_waitcnt vmcnt(22)
	v_bfe_u32 v98, v94, 17, 1
	v_and_b32_e32 v90, 0xfffe0000, v90
	v_add3_u32 v94, v94, v98, s86
	v_and_b32_e32 v94, 0xfffe0000, v94
	v_cvt_pk_bf16_f32 v90, v90, v94
	ds_write_b32 v110, v90 offset:4128
	v_bfe_u32 v90, v91, 17, 1
	v_add3_u32 v90, v91, v90, s86
	v_bfe_u32 v91, v95, 17, 1
	v_and_b32_e32 v90, 0xfffe0000, v90
	v_add3_u32 v91, v95, v91, s86
	v_and_b32_e32 v91, 0xfffe0000, v91
	v_cvt_pk_bf16_f32 v90, v90, v91
	ds_write_b32 v110, v90 offset:4256
	v_bfe_u32 v90, v92, 17, 1
	v_add3_u32 v90, v92, v90, s86
	v_bfe_u32 v91, v96, 17, 1
	v_and_b32_e32 v90, 0xfffe0000, v90
	v_add3_u32 v91, v96, v91, s86
	v_and_b32_e32 v91, 0xfffe0000, v91
	v_cvt_pk_bf16_f32 v90, v90, v91
	ds_write_b32 v110, v90 offset:4384
	v_bfe_u32 v90, v93, 17, 1
	v_add3_u32 v90, v93, v90, s86
	v_bfe_u32 v91, v97, 17, 1
	v_and_b32_e32 v90, 0xfffe0000, v90
	v_add3_u32 v91, v97, v91, s86
	v_and_b32_e32 v91, 0xfffe0000, v91
	v_cvt_pk_bf16_f32 v90, v90, v91
	ds_write_b32 v110, v90 offset:4512
	s_waitcnt vmcnt(21)
	v_bfe_u32 v90, v82, 17, 1
	v_add3_u32 v82, v82, v90, s86
	s_waitcnt vmcnt(20)
	v_bfe_u32 v90, v86, 17, 1
	v_and_b32_e32 v82, 0xfffe0000, v82
	v_add3_u32 v86, v86, v90, s86
	v_and_b32_e32 v86, 0xfffe0000, v86
	v_cvt_pk_bf16_f32 v82, v82, v86
	ds_write_b32 v110, v82 offset:5160
	v_bfe_u32 v82, v83, 17, 1
	v_add3_u32 v82, v83, v82, s86
	v_bfe_u32 v83, v87, 17, 1
	v_and_b32_e32 v82, 0xfffe0000, v82
	v_add3_u32 v83, v87, v83, s86
	v_and_b32_e32 v83, 0xfffe0000, v83
	v_cvt_pk_bf16_f32 v82, v82, v83
	ds_write_b32 v110, v82 offset:5288
	v_bfe_u32 v82, v84, 17, 1
	v_add3_u32 v82, v84, v82, s86
	v_bfe_u32 v83, v88, 17, 1
	v_and_b32_e32 v82, 0xfffe0000, v82
	v_add3_u32 v83, v88, v83, s86
	v_and_b32_e32 v83, 0xfffe0000, v83
	v_cvt_pk_bf16_f32 v82, v82, v83
	ds_write_b32 v110, v82 offset:5416
	v_bfe_u32 v82, v85, 17, 1
	v_add3_u32 v82, v85, v82, s86
	v_bfe_u32 v83, v89, 17, 1
	v_and_b32_e32 v82, 0xfffe0000, v82
	v_add3_u32 v83, v89, v83, s86
	v_and_b32_e32 v83, 0xfffe0000, v83
	v_cvt_pk_bf16_f32 v82, v82, v83
	ds_write_b32 v110, v82 offset:5544
	s_waitcnt vmcnt(19)
	v_bfe_u32 v82, v74, 17, 1
	v_add3_u32 v74, v74, v82, s86
	s_waitcnt vmcnt(18)
	v_bfe_u32 v82, v78, 17, 1
	v_and_b32_e32 v74, 0xfffe0000, v74
	v_add3_u32 v78, v78, v82, s86
	v_and_b32_e32 v78, 0xfffe0000, v78
	v_cvt_pk_bf16_f32 v74, v74, v78
	ds_write_b32 v110, v74 offset:6192
	v_bfe_u32 v74, v75, 17, 1
	v_add3_u32 v74, v75, v74, s86
	v_bfe_u32 v75, v79, 17, 1
	v_and_b32_e32 v74, 0xfffe0000, v74
	v_add3_u32 v75, v79, v75, s86
	v_and_b32_e32 v75, 0xfffe0000, v75
	v_cvt_pk_bf16_f32 v74, v74, v75
	ds_write_b32 v110, v74 offset:6320
	v_bfe_u32 v74, v76, 17, 1
	v_add3_u32 v74, v76, v74, s86
	v_bfe_u32 v75, v80, 17, 1
	v_and_b32_e32 v74, 0xfffe0000, v74
	v_add3_u32 v75, v80, v75, s86
	v_and_b32_e32 v75, 0xfffe0000, v75
	v_cvt_pk_bf16_f32 v74, v74, v75
	ds_write_b32 v110, v74 offset:6448
	v_bfe_u32 v74, v77, 17, 1
	v_add3_u32 v74, v77, v74, s86
	v_bfe_u32 v75, v81, 17, 1
	v_and_b32_e32 v74, 0xfffe0000, v74
	v_add3_u32 v75, v81, v75, s86
	v_and_b32_e32 v75, 0xfffe0000, v75
	v_cvt_pk_bf16_f32 v74, v74, v75
	ds_write_b32 v110, v74 offset:6576
	s_waitcnt vmcnt(17)
	v_bfe_u32 v74, v66, 17, 1
	v_add3_u32 v66, v66, v74, s86
	s_waitcnt vmcnt(16)
	v_bfe_u32 v74, v70, 17, 1
	v_and_b32_e32 v66, 0xfffe0000, v66
	v_add3_u32 v70, v70, v74, s86
	v_and_b32_e32 v70, 0xfffe0000, v70
	v_cvt_pk_bf16_f32 v66, v66, v70
	ds_write_b32 v110, v66 offset:7224
	v_bfe_u32 v66, v67, 17, 1
	v_add3_u32 v66, v67, v66, s86
	v_bfe_u32 v67, v71, 17, 1
	v_and_b32_e32 v66, 0xfffe0000, v66
	v_add3_u32 v67, v71, v67, s86
	v_and_b32_e32 v67, 0xfffe0000, v67
	v_cvt_pk_bf16_f32 v66, v66, v67
	ds_write_b32 v110, v66 offset:7352
	v_bfe_u32 v66, v68, 17, 1
	v_add3_u32 v66, v68, v66, s86
	v_bfe_u32 v67, v72, 17, 1
	v_and_b32_e32 v66, 0xfffe0000, v66
	v_add3_u32 v67, v72, v67, s86
	v_and_b32_e32 v67, 0xfffe0000, v67
	v_cvt_pk_bf16_f32 v66, v66, v67
	ds_write_b32 v110, v66 offset:7480
	v_bfe_u32 v66, v69, 17, 1
	v_add3_u32 v66, v69, v66, s86
	v_bfe_u32 v67, v73, 17, 1
	v_and_b32_e32 v66, 0xfffe0000, v66
	v_add3_u32 v67, v73, v67, s86
	v_and_b32_e32 v67, 0xfffe0000, v67
	v_cvt_pk_bf16_f32 v66, v66, v67
	ds_write_b32 v110, v66 offset:7608
	s_waitcnt vmcnt(15)
	v_bfe_u32 v66, v58, 17, 1
	v_add3_u32 v58, v58, v66, s86
	s_waitcnt vmcnt(14)
	v_bfe_u32 v66, v62, 17, 1
	v_and_b32_e32 v58, 0xfffe0000, v58
	v_add3_u32 v62, v62, v66, s86
	v_and_b32_e32 v62, 0xfffe0000, v62
	v_cvt_pk_bf16_f32 v58, v58, v62
	ds_write_b32 v110, v58 offset:8256
	v_bfe_u32 v58, v59, 17, 1
	v_add3_u32 v58, v59, v58, s86
	v_bfe_u32 v59, v63, 17, 1
	v_and_b32_e32 v58, 0xfffe0000, v58
	v_add3_u32 v59, v63, v59, s86
	v_and_b32_e32 v59, 0xfffe0000, v59
	v_cvt_pk_bf16_f32 v58, v58, v59
	ds_write_b32 v110, v58 offset:8384
	v_bfe_u32 v58, v60, 17, 1
	v_add3_u32 v58, v60, v58, s86
	v_bfe_u32 v59, v64, 17, 1
	v_and_b32_e32 v58, 0xfffe0000, v58
	v_add3_u32 v59, v64, v59, s86
	v_and_b32_e32 v59, 0xfffe0000, v59
	v_cvt_pk_bf16_f32 v58, v58, v59
	ds_write_b32 v110, v58 offset:8512
	v_bfe_u32 v58, v61, 17, 1
	v_add3_u32 v58, v61, v58, s86
	v_bfe_u32 v59, v65, 17, 1
	v_and_b32_e32 v58, 0xfffe0000, v58
	v_add3_u32 v59, v65, v59, s86
	v_and_b32_e32 v59, 0xfffe0000, v59
	v_cvt_pk_bf16_f32 v58, v58, v59
	ds_write_b32 v110, v58 offset:8640
	s_waitcnt vmcnt(13)
	v_bfe_u32 v58, v50, 17, 1
	v_add3_u32 v50, v50, v58, s86
	s_waitcnt vmcnt(12)
	v_bfe_u32 v58, v54, 17, 1
	v_and_b32_e32 v50, 0xfffe0000, v50
	v_add3_u32 v54, v54, v58, s86
	v_and_b32_e32 v54, 0xfffe0000, v54
	v_cvt_pk_bf16_f32 v50, v50, v54
	ds_write_b32 v110, v50 offset:9288
	v_bfe_u32 v50, v51, 17, 1
	v_add3_u32 v50, v51, v50, s86
	v_bfe_u32 v51, v55, 17, 1
	v_and_b32_e32 v50, 0xfffe0000, v50
	v_add3_u32 v51, v55, v51, s86
	v_and_b32_e32 v51, 0xfffe0000, v51
	v_cvt_pk_bf16_f32 v50, v50, v51
	ds_write_b32 v110, v50 offset:9416
	v_bfe_u32 v50, v52, 17, 1
	v_add3_u32 v50, v52, v50, s86
	v_bfe_u32 v51, v56, 17, 1
	v_and_b32_e32 v50, 0xfffe0000, v50
	v_add3_u32 v51, v56, v51, s86
	v_and_b32_e32 v51, 0xfffe0000, v51
	v_cvt_pk_bf16_f32 v50, v50, v51
	ds_write_b32 v110, v50 offset:9544
	v_bfe_u32 v50, v53, 17, 1
	v_add3_u32 v50, v53, v50, s86
	v_bfe_u32 v51, v57, 17, 1
	v_and_b32_e32 v50, 0xfffe0000, v50
	v_add3_u32 v51, v57, v51, s86
	v_and_b32_e32 v51, 0xfffe0000, v51
	v_cvt_pk_bf16_f32 v50, v50, v51
	ds_write_b32 v110, v50 offset:9672
	s_waitcnt vmcnt(11)
	v_bfe_u32 v50, v42, 17, 1
	v_add3_u32 v42, v42, v50, s86
	s_waitcnt vmcnt(10)
	v_bfe_u32 v50, v46, 17, 1
	v_and_b32_e32 v42, 0xfffe0000, v42
	v_add3_u32 v46, v46, v50, s86
	v_and_b32_e32 v46, 0xfffe0000, v46
	v_cvt_pk_bf16_f32 v42, v42, v46
	ds_write_b32 v110, v42 offset:10320
	v_bfe_u32 v42, v43, 17, 1
	v_add3_u32 v42, v43, v42, s86
	v_bfe_u32 v43, v47, 17, 1
	v_and_b32_e32 v42, 0xfffe0000, v42
	v_add3_u32 v43, v47, v43, s86
	v_and_b32_e32 v43, 0xfffe0000, v43
	v_cvt_pk_bf16_f32 v42, v42, v43
	ds_write_b32 v110, v42 offset:10448
	v_bfe_u32 v42, v44, 17, 1
	v_add3_u32 v42, v44, v42, s86
	v_bfe_u32 v43, v48, 17, 1
	v_and_b32_e32 v42, 0xfffe0000, v42
	v_add3_u32 v43, v48, v43, s86
	v_and_b32_e32 v43, 0xfffe0000, v43
	v_cvt_pk_bf16_f32 v42, v42, v43
	ds_write_b32 v110, v42 offset:10576
	v_bfe_u32 v42, v45, 17, 1
	v_add3_u32 v42, v45, v42, s86
	v_bfe_u32 v43, v49, 17, 1
	v_and_b32_e32 v42, 0xfffe0000, v42
	v_add3_u32 v43, v49, v43, s86
	v_and_b32_e32 v43, 0xfffe0000, v43
	v_cvt_pk_bf16_f32 v42, v42, v43
	ds_write_b32 v110, v42 offset:10704
	s_waitcnt vmcnt(9)
	v_bfe_u32 v42, v34, 17, 1
	v_add3_u32 v34, v34, v42, s86
	s_waitcnt vmcnt(8)
	v_bfe_u32 v42, v38, 17, 1
	v_and_b32_e32 v34, 0xfffe0000, v34
	v_add3_u32 v38, v38, v42, s86
	v_and_b32_e32 v38, 0xfffe0000, v38
	v_cvt_pk_bf16_f32 v34, v34, v38
	ds_write_b32 v110, v34 offset:11352
	v_bfe_u32 v34, v35, 17, 1
	v_add3_u32 v34, v35, v34, s86
	v_bfe_u32 v35, v39, 17, 1
	v_and_b32_e32 v34, 0xfffe0000, v34
	v_add3_u32 v35, v39, v35, s86
	v_and_b32_e32 v35, 0xfffe0000, v35
	v_cvt_pk_bf16_f32 v34, v34, v35
	ds_write_b32 v110, v34 offset:11480
	v_bfe_u32 v34, v36, 17, 1
	v_add3_u32 v34, v36, v34, s86
	v_bfe_u32 v35, v40, 17, 1
	v_and_b32_e32 v34, 0xfffe0000, v34
	v_add3_u32 v35, v40, v35, s86
	v_and_b32_e32 v35, 0xfffe0000, v35
	v_cvt_pk_bf16_f32 v34, v34, v35
	ds_write_b32 v110, v34 offset:11608
	v_bfe_u32 v34, v37, 17, 1
	v_add3_u32 v34, v37, v34, s86
	v_bfe_u32 v35, v41, 17, 1
	v_and_b32_e32 v34, 0xfffe0000, v34
	v_add3_u32 v35, v41, v35, s86
	v_and_b32_e32 v35, 0xfffe0000, v35
	v_cvt_pk_bf16_f32 v34, v34, v35
	ds_write_b32 v110, v34 offset:11736
	s_waitcnt vmcnt(7)
	v_bfe_u32 v34, v26, 17, 1
	v_add3_u32 v26, v26, v34, s86
	s_waitcnt vmcnt(6)
	v_bfe_u32 v34, v30, 17, 1
	v_and_b32_e32 v26, 0xfffe0000, v26
	v_add3_u32 v30, v30, v34, s86
	v_and_b32_e32 v30, 0xfffe0000, v30
	v_cvt_pk_bf16_f32 v26, v26, v30
	ds_write_b32 v110, v26 offset:12384
	v_bfe_u32 v26, v27, 17, 1
	v_add3_u32 v26, v27, v26, s86
	v_bfe_u32 v27, v31, 17, 1
	v_and_b32_e32 v26, 0xfffe0000, v26
	v_add3_u32 v27, v31, v27, s86
	v_and_b32_e32 v27, 0xfffe0000, v27
	v_cvt_pk_bf16_f32 v26, v26, v27
	ds_write_b32 v110, v26 offset:12512
	v_bfe_u32 v26, v28, 17, 1
	v_add3_u32 v26, v28, v26, s86
	v_bfe_u32 v27, v32, 17, 1
	v_and_b32_e32 v26, 0xfffe0000, v26
	v_add3_u32 v27, v32, v27, s86
	v_and_b32_e32 v27, 0xfffe0000, v27
	v_cvt_pk_bf16_f32 v26, v26, v27
	ds_write_b32 v110, v26 offset:12640
	v_bfe_u32 v26, v29, 17, 1
	v_add3_u32 v26, v29, v26, s86
	v_bfe_u32 v27, v33, 17, 1
	v_and_b32_e32 v26, 0xfffe0000, v26
	v_add3_u32 v27, v33, v27, s86
	v_and_b32_e32 v27, 0xfffe0000, v27
	v_cvt_pk_bf16_f32 v26, v26, v27
	ds_write_b32 v110, v26 offset:12768
	s_waitcnt vmcnt(5)
	v_bfe_u32 v26, v18, 17, 1
	v_add3_u32 v18, v18, v26, s86
	s_waitcnt vmcnt(4)
	v_bfe_u32 v26, v22, 17, 1
	v_and_b32_e32 v18, 0xfffe0000, v18
	v_add3_u32 v22, v22, v26, s86
	v_and_b32_e32 v22, 0xfffe0000, v22
	v_cvt_pk_bf16_f32 v18, v18, v22
	ds_write_b32 v110, v18 offset:13416
	v_bfe_u32 v18, v19, 17, 1
	v_add3_u32 v18, v19, v18, s86
	v_bfe_u32 v19, v23, 17, 1
	v_and_b32_e32 v18, 0xfffe0000, v18
	v_add3_u32 v19, v23, v19, s86
	v_and_b32_e32 v19, 0xfffe0000, v19
	v_cvt_pk_bf16_f32 v18, v18, v19
	ds_write_b32 v110, v18 offset:13544
	v_bfe_u32 v18, v20, 17, 1
	v_add3_u32 v18, v20, v18, s86
	v_bfe_u32 v19, v24, 17, 1
	v_and_b32_e32 v18, 0xfffe0000, v18
	v_add3_u32 v19, v24, v19, s86
	v_and_b32_e32 v19, 0xfffe0000, v19
	v_cvt_pk_bf16_f32 v18, v18, v19
	ds_write_b32 v110, v18 offset:13672
	v_bfe_u32 v18, v21, 17, 1
	v_add3_u32 v18, v21, v18, s86
	v_bfe_u32 v19, v25, 17, 1
	v_and_b32_e32 v18, 0xfffe0000, v18
	v_add3_u32 v19, v25, v19, s86
	v_and_b32_e32 v19, 0xfffe0000, v19
	v_cvt_pk_bf16_f32 v18, v18, v19
	ds_write_b32 v110, v18 offset:13800
	s_waitcnt vmcnt(3)
	v_bfe_u32 v18, v10, 17, 1
	v_add3_u32 v10, v10, v18, s86
	s_waitcnt vmcnt(2)
	v_bfe_u32 v18, v14, 17, 1
	v_and_b32_e32 v10, 0xfffe0000, v10
	v_add3_u32 v14, v14, v18, s86
	v_and_b32_e32 v14, 0xfffe0000, v14
	v_cvt_pk_bf16_f32 v10, v10, v14
	ds_write_b32 v110, v10 offset:14448
	v_bfe_u32 v10, v11, 17, 1
	v_add3_u32 v10, v11, v10, s86
	v_bfe_u32 v11, v15, 17, 1
	v_and_b32_e32 v10, 0xfffe0000, v10
	v_add3_u32 v11, v15, v11, s86
	v_and_b32_e32 v11, 0xfffe0000, v11
	v_cvt_pk_bf16_f32 v10, v10, v11
	ds_write_b32 v110, v10 offset:14576
	v_bfe_u32 v10, v12, 17, 1
	v_add3_u32 v10, v12, v10, s86
	v_bfe_u32 v11, v16, 17, 1
	v_and_b32_e32 v10, 0xfffe0000, v10
	v_add3_u32 v11, v16, v11, s86
	v_and_b32_e32 v11, 0xfffe0000, v11
	v_cvt_pk_bf16_f32 v10, v10, v11
	ds_write_b32 v110, v10 offset:14704
	v_bfe_u32 v10, v13, 17, 1
	v_add3_u32 v10, v13, v10, s86
	v_bfe_u32 v11, v17, 17, 1
	v_and_b32_e32 v10, 0xfffe0000, v10
	v_add3_u32 v11, v17, v11, s86
	v_and_b32_e32 v11, 0xfffe0000, v11
	v_cvt_pk_bf16_f32 v10, v10, v11
	ds_write_b32 v110, v10 offset:14832
	s_waitcnt vmcnt(1)
	v_bfe_u32 v10, v2, 17, 1
	v_add3_u32 v2, v2, v10, s86
	s_waitcnt vmcnt(0)
	v_bfe_u32 v10, v6, 17, 1
	v_and_b32_e32 v2, 0xfffe0000, v2
	v_add3_u32 v6, v6, v10, s86
	v_and_b32_e32 v6, 0xfffe0000, v6
	v_cvt_pk_bf16_f32 v2, v2, v6
	ds_write_b32 v110, v2 offset:15480
	v_bfe_u32 v2, v3, 17, 1
	v_add3_u32 v2, v3, v2, s86
	v_bfe_u32 v3, v7, 17, 1
	v_and_b32_e32 v2, 0xfffe0000, v2
	v_add3_u32 v3, v7, v3, s86
	v_and_b32_e32 v3, 0xfffe0000, v3
	v_cvt_pk_bf16_f32 v2, v2, v3
	ds_write_b32 v110, v2 offset:15608
	v_bfe_u32 v2, v4, 17, 1
	v_add3_u32 v2, v4, v2, s86
	v_bfe_u32 v3, v8, 17, 1
	v_and_b32_e32 v2, 0xfffe0000, v2
	v_add3_u32 v3, v8, v3, s86
	v_and_b32_e32 v3, 0xfffe0000, v3
	v_cvt_pk_bf16_f32 v2, v2, v3
	ds_write_b32 v110, v2 offset:15736
	v_bfe_u32 v2, v5, 17, 1
	v_add3_u32 v2, v5, v2, s86
	v_bfe_u32 v3, v9, 17, 1
	v_and_b32_e32 v2, 0xfffe0000, v2
	v_add3_u32 v3, v9, v3, s86
	v_and_b32_e32 v3, 0xfffe0000, v3
	v_cvt_pk_bf16_f32 v2, v2, v3
	ds_write_b32 v110, v2 offset:15864
	s_waitcnt lgkmcnt(0)
	ds_read2_b32 v[20:21], v146 offset1:8
	ds_read2_b32 v[4:5], v146 offset0:129 offset1:137
	v_add_u32_e32 v30, 0x400, v146
	ds_read2_b32 v[22:23], v30 offset0:2 offset1:10
	ds_read2_b32 v[6:7], v30 offset0:131 offset1:139
	v_add_u32_e32 v32, 0x400, v147
	ds_read2_b32 v[24:25], v147 offset1:8
	ds_read2_b32 v[12:13], v147 offset0:129 offset1:137
	ds_read2_b32 v[26:27], v32 offset0:2 offset1:10
	ds_read2_b32 v[14:15], v32 offset0:131 offset1:139
	v_or_b32_e32 v31, s44, v131
	v_lshl_add_u64 v[2:3], s[40:41], 0, v[132:133]
	s_waitcnt lgkmcnt(6)
	v_mov_b32_e32 v9, v4
	v_or3_b32 v4, v31, v145, s2
	v_or_b32_e32 v33, s44, v144
	v_lshl_add_u64 v[2:3], v[2:3], 0, s[4:5]
	v_lshlrev_b32_e32 v132, 7, v4
	v_or3_b32 v4, v33, v145, s2
	v_mov_b32_e32 v8, v20
	s_waitcnt lgkmcnt(5)
	v_mov_b32_e32 v10, v22
	s_waitcnt lgkmcnt(4)
	v_mov_b32_e32 v11, v6
	v_lshl_add_u64 v[16:17], v[2:3], 0, v[132:133]
	v_lshlrev_b32_e32 v132, 7, v4
	global_store_dwordx4 v[16:17], v[8:11], off
	v_lshl_add_u64 v[16:17], v[2:3], 0, v[132:133]
	v_add_u32_e32 v4, 0x400, v149
	s_waitcnt lgkmcnt(3)
	v_mov_b32_e32 v8, v24
	s_waitcnt lgkmcnt(2)
	v_mov_b32_e32 v9, v12
	s_waitcnt lgkmcnt(1)
	v_mov_b32_e32 v10, v26
	s_waitcnt lgkmcnt(0)
	v_mov_b32_e32 v11, v14
	global_store_dwordx4 v[16:17], v[8:11], off
	ds_read2_b32 v[10:11], v4 offset0:2 offset1:131
	v_or3_b32 v4, v31, v148, s2
	ds_read2_b32 v[8:9], v149 offset1:129
	v_lshlrev_b32_e32 v132, 7, v4
	v_add_u32_e32 v4, 0x400, v150
	ds_read2_b32 v[16:17], v150 offset1:129
	ds_read2_b32 v[18:19], v4 offset0:2 offset1:131
	v_or3_b32 v4, v33, v148, s2
	v_lshl_add_u64 v[28:29], v[2:3], 0, v[132:133]
	v_lshlrev_b32_e32 v132, 7, v4
	s_waitcnt lgkmcnt(2)
	global_store_dwordx4 v[28:29], v[8:11], off
	v_mov_b32_e32 v4, v21
	v_mov_b32_e32 v6, v23
	v_lshl_add_u64 v[8:9], v[2:3], 0, v[132:133]
	s_waitcnt lgkmcnt(0)
	global_store_dwordx4 v[8:9], v[16:19], off
	v_or3_b32 v8, v31, v151, s2
	v_lshlrev_b32_e32 v132, 7, v8
	v_lshl_add_u64 v[8:9], v[2:3], 0, v[132:133]
	global_store_dwordx4 v[8:9], v[4:7], off
	v_mov_b32_e32 v12, v25
	v_mov_b32_e32 v14, v27
	v_or3_b32 v4, v33, v151, s2
	v_add_u32_e32 v6, 0x400, v153
	v_lshlrev_b32_e32 v132, 7, v4
	ds_read2_b32 v[4:5], v153 offset1:129
	ds_read2_b32 v[6:7], v6 offset0:2 offset1:131
	v_lshl_add_u64 v[8:9], v[2:3], 0, v[132:133]
	global_store_dwordx4 v[8:9], v[12:15], off
	v_or3_b32 v8, v31, v152, s2
	v_lshlrev_b32_e32 v132, 7, v8
	v_lshl_add_u64 v[8:9], v[2:3], 0, v[132:133]
	s_waitcnt lgkmcnt(0)
	global_store_dwordx4 v[8:9], v[4:7], off
	ds_read2_b32 v[4:5], v154 offset1:129
	v_or3_b32 v8, v33, v152, s2
	v_add_u32_e32 v6, 0x400, v154
	ds_read2_b32 v[6:7], v6 offset0:2 offset1:131
	v_lshlrev_b32_e32 v132, 7, v8
	v_lshl_add_u64 v[12:13], v[2:3], 0, v[132:133]
	ds_read2_b32 v[20:21], v146 offset0:16 offset1:24
	ds_read2_b32 v[8:9], v146 offset0:145 offset1:153
	ds_read2_b32 v[22:23], v30 offset0:18 offset1:26
	ds_read2_b32 v[10:11], v30 offset0:147 offset1:155
	s_waitcnt lgkmcnt(4)
	global_store_dwordx4 v[12:13], v[4:7], off
	ds_read2_b32 v[24:25], v147 offset0:16 offset1:24
	ds_read2_b32 v[12:13], v147 offset0:145 offset1:153
	ds_read2_b32 v[26:27], v32 offset0:18 offset1:26
	ds_read2_b32 v[14:15], v32 offset0:147 offset1:155
	s_waitcnt lgkmcnt(6)
	v_mov_b32_e32 v5, v8
	v_or3_b32 v8, v31, v155, s2
	v_lshlrev_b32_e32 v132, 7, v8
	v_or3_b32 v8, v33, v155, s2
	v_mov_b32_e32 v4, v20
	s_waitcnt lgkmcnt(5)
	v_mov_b32_e32 v6, v22
	s_waitcnt lgkmcnt(4)
	v_mov_b32_e32 v7, v10
	v_lshl_add_u64 v[16:17], v[2:3], 0, v[132:133]
	v_lshlrev_b32_e32 v132, 7, v8
	global_store_dwordx4 v[16:17], v[4:7], off
	v_lshl_add_u64 v[16:17], v[2:3], 0, v[132:133]
	v_or3_b32 v8, v31, v158, s2
	s_waitcnt lgkmcnt(3)
	v_mov_b32_e32 v4, v24
	s_waitcnt lgkmcnt(2)
	v_mov_b32_e32 v5, v12
	s_waitcnt lgkmcnt(1)
	v_mov_b32_e32 v6, v26
	s_waitcnt lgkmcnt(0)
	v_mov_b32_e32 v7, v14
	global_store_dwordx4 v[16:17], v[4:7], off
	ds_read2_b32 v[4:5], v159 offset1:129
	v_lshlrev_b32_e32 v132, 7, v8
	v_add_u32_e32 v6, 0x400, v159
	ds_read2_b32 v[6:7], v6 offset0:2 offset1:131
	v_add_u32_e32 v8, 0x400, v160
	ds_read2_b32 v[16:17], v160 offset1:129
	ds_read2_b32 v[18:19], v8 offset0:2 offset1:131
	v_lshl_add_u64 v[28:29], v[2:3], 0, v[132:133]
	s_waitcnt lgkmcnt(2)
	global_store_dwordx4 v[28:29], v[4:7], off
	v_mov_b32_e32 v8, v21
	v_mov_b32_e32 v10, v23
	v_or3_b32 v4, v33, v158, s2
	v_lshlrev_b32_e32 v132, 7, v4
	v_lshl_add_u64 v[4:5], v[2:3], 0, v[132:133]
	s_waitcnt lgkmcnt(0)
	global_store_dwordx4 v[4:5], v[16:19], off
	v_or3_b32 v4, v31, v161, s2
	v_lshlrev_b32_e32 v132, 7, v4
	v_lshl_add_u64 v[4:5], v[2:3], 0, v[132:133]
	global_store_dwordx4 v[4:5], v[8:11], off
	v_or3_b32 v4, v33, v161, s2
	v_lshlrev_b32_e32 v132, 7, v4
	v_mov_b32_e32 v12, v25
	v_mov_b32_e32 v14, v27
	v_lshl_add_u64 v[4:5], v[2:3], 0, v[132:133]
	v_add_u32_e32 v6, 0x400, v163
	global_store_dwordx4 v[4:5], v[12:15], off
	ds_read2_b32 v[4:5], v163 offset1:129
	ds_read2_b32 v[6:7], v6 offset0:2 offset1:131
	v_or3_b32 v8, v31, v162, s2
	v_add_u32_e32 v10, 0x400, v164
	v_lshlrev_b32_e32 v132, 7, v8
	ds_read2_b32 v[8:9], v164 offset1:129
	ds_read2_b32 v[10:11], v10 offset0:2 offset1:131
	v_lshl_add_u64 v[12:13], v[2:3], 0, v[132:133]
	s_waitcnt lgkmcnt(2)
	global_store_dwordx4 v[12:13], v[4:7], off
	s_nop 1
	v_or3_b32 v4, v33, v162, s2
	v_lshlrev_b32_e32 v132, 7, v4
	v_lshl_add_u64 v[2:3], v[2:3], 0, v[132:133]
	s_waitcnt lgkmcnt(0)
	global_store_dwordx4 v[2:3], v[8:11], off
	s_waitcnt lgkmcnt(0)

.LBB0_23:
	s_andn2_b64 vcc, exec, s[4:5]
	s_cbranch_vccnz .LBB0_25
	s_mul_i32 s4, s42, 0x2c00000
	s_mul_hi_i32 s2, s42, 0x2c00000
	s_add_u32 s44, s24, s4
	s_addc_u32 s45, s25, s2
	s_add_i32 s2, s70, 0xe680
	s_bfe_u32 s4, s2, 0xc0004
	v_lshlrev_b32_e32 v2, 2, v135
	s_and_b32 s2, s46, 0x780
	v_lshl_or_b32 v132, s4, 19, v2
	v_lshl_add_u64 v[2:3], s[44:45], 0, v[132:133]
	s_lshl_b32 s38, s2, 2
	v_lshl_add_u64 v[2:3], v[2:3], 0, s[38:39]
	v_lshlrev_b32_e32 v132, 2, v130
	v_lshl_add_u64 v[2:3], v[2:3], 0, v[132:133]
	v_add_co_u32_e32 v4, vcc, s68, v2
	s_mov_b32 s5, 0x8000
	s_nop 0
	v_addc_co_u32_e32 v5, vcc, 0, v3, vcc
	global_load_dwordx4 v[106:109], v[2:3], off nt
	global_load_dwordx4 v[110:113], v[4:5], off nt
	v_add_co_u32_e32 v4, vcc, s5, v2
	s_mov_b32 s5, 0xa000
	s_nop 0
	v_addc_co_u32_e32 v5, vcc, 0, v3, vcc
	v_add_co_u32_e32 v6, vcc, s5, v2
	s_mov_b32 s5, 0x10000
	s_nop 0
	v_addc_co_u32_e32 v7, vcc, 0, v3, vcc
	global_load_dwordx4 v[114:117], v[4:5], off nt
	global_load_dwordx4 v[118:121], v[6:7], off nt
	v_add_co_u32_e32 v4, vcc, s5, v2
	s_mov_b32 s5, 0x12000
	s_nop 0
	v_addc_co_u32_e32 v5, vcc, 0, v3, vcc
	v_add_co_u32_e32 v6, vcc, s5, v2
	s_mov_b32 s5, 0x18000
	s_nop 0
	v_addc_co_u32_e32 v7, vcc, 0, v3, vcc
	global_load_dwordx4 v[122:125], v[4:5], off nt
	global_load_dwordx4 v[126:129], v[6:7], off nt
	v_add_co_u32_e32 v4, vcc, s5, v2
	s_mov_b32 s5, 0x1a000
	s_nop 0
	v_addc_co_u32_e32 v5, vcc, 0, v3, vcc
	v_add_co_u32_e32 v6, vcc, s5, v2
	s_mov_b32 s5, 0x20000
	s_nop 0
	v_addc_co_u32_e32 v7, vcc, 0, v3, vcc
	global_load_dwordx4 v[98:101], v[4:5], off nt
	global_load_dwordx4 v[102:105], v[6:7], off nt
	v_add_co_u32_e32 v4, vcc, s5, v2
	s_mov_b32 s5, 0x22000
	s_nop 0
	v_addc_co_u32_e32 v5, vcc, 0, v3, vcc
	v_add_co_u32_e32 v6, vcc, s5, v2
	s_mov_b32 s5, 0x28000
	s_nop 0
	v_addc_co_u32_e32 v7, vcc, 0, v3, vcc
	global_load_dwordx4 v[90:93], v[4:5], off nt
	global_load_dwordx4 v[94:97], v[6:7], off nt
	v_add_co_u32_e32 v4, vcc, s5, v2
	s_mov_b32 s5, 0x30000
	s_nop 0
	v_addc_co_u32_e32 v5, vcc, 0, v3, vcc
	v_add_co_u32_e32 v6, vcc, s58, v2
	s_lshl_b32 s4, s4, 11
	s_nop 0
	v_addc_co_u32_e32 v7, vcc, 0, v3, vcc
	global_load_dwordx4 v[82:85], v[4:5], off nt
	global_load_dwordx4 v[86:89], v[6:7], off nt
	v_add_co_u32_e32 v4, vcc, s5, v2
	s_mov_b32 s5, 0x32000
	s_nop 0
	v_addc_co_u32_e32 v5, vcc, 0, v3, vcc
	v_add_co_u32_e32 v6, vcc, s5, v2
	s_mov_b32 s5, 0x3a000
	s_nop 0
	v_addc_co_u32_e32 v7, vcc, 0, v3, vcc
	global_load_dwordx4 v[74:77], v[4:5], off nt
	global_load_dwordx4 v[78:81], v[6:7], off nt
	v_add_co_u32_e32 v4, vcc, s61, v2
	s_mov_b64 s[44:45], 0x2c00000
	s_nop 0
	v_addc_co_u32_e32 v5, vcc, 0, v3, vcc
	v_add_co_u32_e32 v6, vcc, s5, v2
	s_mov_b32 s5, 0x40000
	s_nop 0
	v_addc_co_u32_e32 v7, vcc, 0, v3, vcc
	global_load_dwordx4 v[66:69], v[4:5], off nt
	global_load_dwordx4 v[70:73], v[6:7], off nt
	v_add_co_u32_e32 v4, vcc, s5, v2
	s_mov_b32 s5, 0x42000
	s_nop 0
	v_addc_co_u32_e32 v5, vcc, 0, v3, vcc
	v_add_co_u32_e32 v6, vcc, s5, v2
	s_mov_b32 s5, 0x48000
	s_nop 0
	v_addc_co_u32_e32 v7, vcc, 0, v3, vcc
	global_load_dwordx4 v[58:61], v[4:5], off nt
	global_load_dwordx4 v[62:65], v[6:7], off nt
	v_add_co_u32_e32 v4, vcc, s5, v2
	s_mov_b32 s5, 0x4a000
	s_nop 0
	v_addc_co_u32_e32 v5, vcc, 0, v3, vcc
	v_add_co_u32_e32 v6, vcc, s5, v2
	s_mov_b32 s5, 0x50000
	s_nop 0
	v_addc_co_u32_e32 v7, vcc, 0, v3, vcc
	global_load_dwordx4 v[50:53], v[4:5], off nt
	global_load_dwordx4 v[54:57], v[6:7], off nt
	v_add_co_u32_e32 v4, vcc, s5, v2
	s_waitcnt vmcnt(19)
	v_bfe_u32 v132, v106, 17, 1
	v_addc_co_u32_e32 v5, vcc, 0, v3, vcc
	v_add_co_u32_e32 v6, vcc, s75, v2
	v_add3_u32 v106, v106, v132, s86
	s_nop 0
	v_addc_co_u32_e32 v7, vcc, 0, v3, vcc
	global_load_dwordx4 v[42:45], v[4:5], off nt
	global_load_dwordx4 v[46:49], v[6:7], off nt
	v_add_co_u32_e32 v4, vcc, s76, v2
	s_waitcnt vmcnt(20)
	v_bfe_u32 v132, v110, 17, 1
	v_addc_co_u32_e32 v5, vcc, 0, v3, vcc
	v_add_co_u32_e32 v6, vcc, s77, v2
	v_add3_u32 v110, v110, v132, s86
	s_nop 0
	v_addc_co_u32_e32 v7, vcc, 0, v3, vcc
	global_load_dwordx4 v[34:37], v[4:5], off nt
	global_load_dwordx4 v[38:41], v[6:7], off nt
	v_add_co_u32_e32 v4, vcc, s78, v2
	v_and_b32_e32 v106, 0xfffe0000, v106
	s_nop 0
	v_addc_co_u32_e32 v5, vcc, 0, v3, vcc
	v_add_co_u32_e32 v6, vcc, s79, v2
	v_and_b32_e32 v110, 0xfffe0000, v110
	s_nop 0
	v_addc_co_u32_e32 v7, vcc, 0, v3, vcc
	global_load_dwordx4 v[26:29], v[4:5], off nt
	global_load_dwordx4 v[30:33], v[6:7], off nt
	v_add_co_u32_e32 v4, vcc, s80, v2
	v_lshlrev_b32_e32 v132, 1, v134
	s_nop 0
	v_addc_co_u32_e32 v5, vcc, 0, v3, vcc
	v_add_co_u32_e32 v6, vcc, s81, v2
	s_nop 1
	v_addc_co_u32_e32 v7, vcc, 0, v3, vcc
	global_load_dwordx4 v[18:21], v[4:5], off nt
	global_load_dwordx4 v[22:25], v[6:7], off nt
	v_add_co_u32_e32 v4, vcc, s82, v2
	s_nop 1
	v_addc_co_u32_e32 v5, vcc, 0, v3, vcc
	v_add_co_u32_e32 v6, vcc, s83, v2
	s_nop 1
	v_addc_co_u32_e32 v7, vcc, 0, v3, vcc
	global_load_dwordx4 v[10:13], v[4:5], off nt
	global_load_dwordx4 v[14:17], v[6:7], off nt
	v_add_co_u32_e32 v4, vcc, s84, v2
	s_nop 1
	v_addc_co_u32_e32 v5, vcc, 0, v3, vcc
	v_add_co_u32_e32 v6, vcc, s85, v2
	s_nop 1
	v_addc_co_u32_e32 v7, vcc, 0, v3, vcc
	global_load_dwordx4 v[2:5], v[4:5], off nt
	s_nop 0
	global_load_dwordx4 v[6:9], v[6:7], off nt
	v_cvt_pk_bf16_f32 v106, v106, v110
	v_add_u32_e32 v110, v142, v143
	ds_write_b32 v110, v106
	v_bfe_u32 v106, v107, 17, 1
	v_add3_u32 v106, v107, v106, s86
	v_bfe_u32 v107, v111, 17, 1
	v_and_b32_e32 v106, 0xfffe0000, v106
	v_add3_u32 v107, v111, v107, s86
	v_and_b32_e32 v107, 0xfffe0000, v107
	v_cvt_pk_bf16_f32 v106, v106, v107
	ds_write_b32 v110, v106 offset:128
	v_bfe_u32 v106, v108, 17, 1
	v_add3_u32 v106, v108, v106, s86
	v_bfe_u32 v107, v112, 17, 1
	v_and_b32_e32 v106, 0xfffe0000, v106
	v_add3_u32 v107, v112, v107, s86
	v_and_b32_e32 v107, 0xfffe0000, v107
	v_cvt_pk_bf16_f32 v106, v106, v107
	ds_write_b32 v110, v106 offset:256
	v_bfe_u32 v106, v109, 17, 1
	v_add3_u32 v106, v109, v106, s86
	v_bfe_u32 v107, v113, 17, 1
	v_and_b32_e32 v106, 0xfffe0000, v106
	v_add3_u32 v107, v113, v107, s86
	v_and_b32_e32 v107, 0xfffe0000, v107
	v_cvt_pk_bf16_f32 v106, v106, v107
	ds_write_b32 v110, v106 offset:384
	s_waitcnt vmcnt(29)
	v_bfe_u32 v106, v114, 17, 1
	v_add3_u32 v106, v114, v106, s86
	s_waitcnt vmcnt(28)
	v_bfe_u32 v107, v118, 17, 1
	v_and_b32_e32 v106, 0xfffe0000, v106
	v_add3_u32 v107, v118, v107, s86
	v_and_b32_e32 v107, 0xfffe0000, v107
	v_cvt_pk_bf16_f32 v106, v106, v107
	ds_write_b32 v110, v106 offset:1032
	v_bfe_u32 v106, v115, 17, 1
	v_add3_u32 v106, v115, v106, s86
	v_bfe_u32 v107, v119, 17, 1
	v_and_b32_e32 v106, 0xfffe0000, v106
	v_add3_u32 v107, v119, v107, s86
	v_and_b32_e32 v107, 0xfffe0000, v107
	v_cvt_pk_bf16_f32 v106, v106, v107
	ds_write_b32 v110, v106 offset:1160
	v_bfe_u32 v106, v116, 17, 1
	v_add3_u32 v106, v116, v106, s86
	v_bfe_u32 v107, v120, 17, 1
	v_and_b32_e32 v106, 0xfffe0000, v106
	v_add3_u32 v107, v120, v107, s86
	v_and_b32_e32 v107, 0xfffe0000, v107
	v_cvt_pk_bf16_f32 v106, v106, v107
	ds_write_b32 v110, v106 offset:1288
	v_bfe_u32 v106, v117, 17, 1
	v_add3_u32 v106, v117, v106, s86
	v_bfe_u32 v107, v121, 17, 1
	v_and_b32_e32 v106, 0xfffe0000, v106
	v_add3_u32 v107, v121, v107, s86
	v_and_b32_e32 v107, 0xfffe0000, v107
	v_cvt_pk_bf16_f32 v106, v106, v107
	ds_write_b32 v110, v106 offset:1416
	s_waitcnt vmcnt(27)
	v_bfe_u32 v106, v122, 17, 1
	v_add3_u32 v106, v122, v106, s86
	s_waitcnt vmcnt(26)
	v_bfe_u32 v107, v126, 17, 1
	v_and_b32_e32 v106, 0xfffe0000, v106
	v_add3_u32 v107, v126, v107, s86
	v_and_b32_e32 v107, 0xfffe0000, v107
	v_cvt_pk_bf16_f32 v106, v106, v107
	ds_write_b32 v110, v106 offset:2064
	v_bfe_u32 v106, v123, 17, 1
	v_add3_u32 v106, v123, v106, s86
	v_bfe_u32 v107, v127, 17, 1
	v_and_b32_e32 v106, 0xfffe0000, v106
	v_add3_u32 v107, v127, v107, s86
	v_and_b32_e32 v107, 0xfffe0000, v107
	v_cvt_pk_bf16_f32 v106, v106, v107
	ds_write_b32 v110, v106 offset:2192
	v_bfe_u32 v106, v124, 17, 1
	v_add3_u32 v106, v124, v106, s86
	v_bfe_u32 v107, v128, 17, 1
	v_and_b32_e32 v106, 0xfffe0000, v106
	v_add3_u32 v107, v128, v107, s86
	v_and_b32_e32 v107, 0xfffe0000, v107
	v_cvt_pk_bf16_f32 v106, v106, v107
	ds_write_b32 v110, v106 offset:2320
	v_bfe_u32 v106, v125, 17, 1
	v_add3_u32 v106, v125, v106, s86
	v_bfe_u32 v107, v129, 17, 1
	v_and_b32_e32 v106, 0xfffe0000, v106
	v_add3_u32 v107, v129, v107, s86
	v_and_b32_e32 v107, 0xfffe0000, v107
	v_cvt_pk_bf16_f32 v106, v106, v107
	ds_write_b32 v110, v106 offset:2448
	s_waitcnt vmcnt(25)
	v_bfe_u32 v106, v98, 17, 1
	v_add3_u32 v98, v98, v106, s86
	s_waitcnt vmcnt(24)
	v_bfe_u32 v106, v102, 17, 1
	v_and_b32_e32 v98, 0xfffe0000, v98
	v_add3_u32 v102, v102, v106, s86
	v_and_b32_e32 v102, 0xfffe0000, v102
	v_cvt_pk_bf16_f32 v98, v98, v102
	ds_write_b32 v110, v98 offset:3096
	v_bfe_u32 v98, v99, 17, 1
	v_add3_u32 v98, v99, v98, s86
	v_bfe_u32 v99, v103, 17, 1
	v_and_b32_e32 v98, 0xfffe0000, v98
	v_add3_u32 v99, v103, v99, s86
	v_and_b32_e32 v99, 0xfffe0000, v99
	v_cvt_pk_bf16_f32 v98, v98, v99
	ds_write_b32 v110, v98 offset:3224
	v_bfe_u32 v98, v100, 17, 1
	v_add3_u32 v98, v100, v98, s86
	v_bfe_u32 v99, v104, 17, 1
	v_and_b32_e32 v98, 0xfffe0000, v98
	v_add3_u32 v99, v104, v99, s86
	v_and_b32_e32 v99, 0xfffe0000, v99
	v_cvt_pk_bf16_f32 v98, v98, v99
	ds_write_b32 v110, v98 offset:3352
	v_bfe_u32 v98, v101, 17, 1
	v_add3_u32 v98, v101, v98, s86
	v_bfe_u32 v99, v105, 17, 1
	v_and_b32_e32 v98, 0xfffe0000, v98
	v_add3_u32 v99, v105, v99, s86
	v_and_b32_e32 v99, 0xfffe0000, v99
	v_cvt_pk_bf16_f32 v98, v98, v99
	ds_write_b32 v110, v98 offset:3480
	s_waitcnt vmcnt(23)
	v_bfe_u32 v98, v90, 17, 1
	v_add3_u32 v90, v90, v98, s86
	s_waitcnt vmcnt(22)
	v_bfe_u32 v98, v94, 17, 1
	v_and_b32_e32 v90, 0xfffe0000, v90
	v_add3_u32 v94, v94, v98, s86
	v_and_b32_e32 v94, 0xfffe0000, v94
	v_cvt_pk_bf16_f32 v90, v90, v94
	ds_write_b32 v110, v90 offset:4128
	v_bfe_u32 v90, v91, 17, 1
	v_add3_u32 v90, v91, v90, s86
	v_bfe_u32 v91, v95, 17, 1
	v_and_b32_e32 v90, 0xfffe0000, v90
	v_add3_u32 v91, v95, v91, s86
	v_and_b32_e32 v91, 0xfffe0000, v91
	v_cvt_pk_bf16_f32 v90, v90, v91
	ds_write_b32 v110, v90 offset:4256
	v_bfe_u32 v90, v92, 17, 1
	v_add3_u32 v90, v92, v90, s86
	v_bfe_u32 v91, v96, 17, 1
	v_and_b32_e32 v90, 0xfffe0000, v90
	v_add3_u32 v91, v96, v91, s86
	v_and_b32_e32 v91, 0xfffe0000, v91
	v_cvt_pk_bf16_f32 v90, v90, v91
	ds_write_b32 v110, v90 offset:4384
	v_bfe_u32 v90, v93, 17, 1
	v_add3_u32 v90, v93, v90, s86
	v_bfe_u32 v91, v97, 17, 1
	v_and_b32_e32 v90, 0xfffe0000, v90
	v_add3_u32 v91, v97, v91, s86
	v_and_b32_e32 v91, 0xfffe0000, v91
	v_cvt_pk_bf16_f32 v90, v90, v91
	ds_write_b32 v110, v90 offset:4512
	s_waitcnt vmcnt(21)
	v_bfe_u32 v90, v82, 17, 1
	v_add3_u32 v82, v82, v90, s86
	s_waitcnt vmcnt(20)
	v_bfe_u32 v90, v86, 17, 1
	v_and_b32_e32 v82, 0xfffe0000, v82
	v_add3_u32 v86, v86, v90, s86
	v_and_b32_e32 v86, 0xfffe0000, v86
	v_cvt_pk_bf16_f32 v82, v82, v86
	ds_write_b32 v110, v82 offset:5160
	v_bfe_u32 v82, v83, 17, 1
	v_add3_u32 v82, v83, v82, s86
	v_bfe_u32 v83, v87, 17, 1
	v_and_b32_e32 v82, 0xfffe0000, v82
	v_add3_u32 v83, v87, v83, s86
	v_and_b32_e32 v83, 0xfffe0000, v83
	v_cvt_pk_bf16_f32 v82, v82, v83
	ds_write_b32 v110, v82 offset:5288
	v_bfe_u32 v82, v84, 17, 1
	v_add3_u32 v82, v84, v82, s86
	v_bfe_u32 v83, v88, 17, 1
	v_and_b32_e32 v82, 0xfffe0000, v82
	v_add3_u32 v83, v88, v83, s86
	v_and_b32_e32 v83, 0xfffe0000, v83
	v_cvt_pk_bf16_f32 v82, v82, v83
	ds_write_b32 v110, v82 offset:5416
	v_bfe_u32 v82, v85, 17, 1
	v_add3_u32 v82, v85, v82, s86
	v_bfe_u32 v83, v89, 17, 1
	v_and_b32_e32 v82, 0xfffe0000, v82
	v_add3_u32 v83, v89, v83, s86
	v_and_b32_e32 v83, 0xfffe0000, v83
	v_cvt_pk_bf16_f32 v82, v82, v83
	ds_write_b32 v110, v82 offset:5544
	s_waitcnt vmcnt(19)
	v_bfe_u32 v82, v74, 17, 1
	v_add3_u32 v74, v74, v82, s86
	s_waitcnt vmcnt(18)
	v_bfe_u32 v82, v78, 17, 1
	v_and_b32_e32 v74, 0xfffe0000, v74
	v_add3_u32 v78, v78, v82, s86
	v_and_b32_e32 v78, 0xfffe0000, v78
	v_cvt_pk_bf16_f32 v74, v74, v78
	ds_write_b32 v110, v74 offset:6192
	v_bfe_u32 v74, v75, 17, 1
	v_add3_u32 v74, v75, v74, s86
	v_bfe_u32 v75, v79, 17, 1
	v_and_b32_e32 v74, 0xfffe0000, v74
	v_add3_u32 v75, v79, v75, s86
	v_and_b32_e32 v75, 0xfffe0000, v75
	v_cvt_pk_bf16_f32 v74, v74, v75
	ds_write_b32 v110, v74 offset:6320
	v_bfe_u32 v74, v76, 17, 1
	v_add3_u32 v74, v76, v74, s86
	v_bfe_u32 v75, v80, 17, 1
	v_and_b32_e32 v74, 0xfffe0000, v74
	v_add3_u32 v75, v80, v75, s86
	v_and_b32_e32 v75, 0xfffe0000, v75
	v_cvt_pk_bf16_f32 v74, v74, v75
	ds_write_b32 v110, v74 offset:6448
	v_bfe_u32 v74, v77, 17, 1
	v_add3_u32 v74, v77, v74, s86
	v_bfe_u32 v75, v81, 17, 1
	v_and_b32_e32 v74, 0xfffe0000, v74
	v_add3_u32 v75, v81, v75, s86
	v_and_b32_e32 v75, 0xfffe0000, v75
	v_cvt_pk_bf16_f32 v74, v74, v75
	ds_write_b32 v110, v74 offset:6576
	s_waitcnt vmcnt(17)
	v_bfe_u32 v74, v66, 17, 1
	v_add3_u32 v66, v66, v74, s86
	s_waitcnt vmcnt(16)
	v_bfe_u32 v74, v70, 17, 1
	v_and_b32_e32 v66, 0xfffe0000, v66
	v_add3_u32 v70, v70, v74, s86
	v_and_b32_e32 v70, 0xfffe0000, v70
	v_cvt_pk_bf16_f32 v66, v66, v70
	ds_write_b32 v110, v66 offset:7224
	v_bfe_u32 v66, v67, 17, 1
	v_add3_u32 v66, v67, v66, s86
	v_bfe_u32 v67, v71, 17, 1
	v_and_b32_e32 v66, 0xfffe0000, v66
	v_add3_u32 v67, v71, v67, s86
	v_and_b32_e32 v67, 0xfffe0000, v67
	v_cvt_pk_bf16_f32 v66, v66, v67
	ds_write_b32 v110, v66 offset:7352
	v_bfe_u32 v66, v68, 17, 1
	v_add3_u32 v66, v68, v66, s86
	v_bfe_u32 v67, v72, 17, 1
	v_and_b32_e32 v66, 0xfffe0000, v66
	v_add3_u32 v67, v72, v67, s86
	v_and_b32_e32 v67, 0xfffe0000, v67
	v_cvt_pk_bf16_f32 v66, v66, v67
	ds_write_b32 v110, v66 offset:7480
	v_bfe_u32 v66, v69, 17, 1
	v_add3_u32 v66, v69, v66, s86
	v_bfe_u32 v67, v73, 17, 1
	v_and_b32_e32 v66, 0xfffe0000, v66
	v_add3_u32 v67, v73, v67, s86
	v_and_b32_e32 v67, 0xfffe0000, v67
	v_cvt_pk_bf16_f32 v66, v66, v67
	ds_write_b32 v110, v66 offset:7608
	s_waitcnt vmcnt(15)
	v_bfe_u32 v66, v58, 17, 1
	v_add3_u32 v58, v58, v66, s86
	s_waitcnt vmcnt(14)
	v_bfe_u32 v66, v62, 17, 1
	v_and_b32_e32 v58, 0xfffe0000, v58
	v_add3_u32 v62, v62, v66, s86
	v_and_b32_e32 v62, 0xfffe0000, v62
	v_cvt_pk_bf16_f32 v58, v58, v62
	ds_write_b32 v110, v58 offset:8256
	v_bfe_u32 v58, v59, 17, 1
	v_add3_u32 v58, v59, v58, s86
	v_bfe_u32 v59, v63, 17, 1
	v_and_b32_e32 v58, 0xfffe0000, v58
	v_add3_u32 v59, v63, v59, s86
	v_and_b32_e32 v59, 0xfffe0000, v59
	v_cvt_pk_bf16_f32 v58, v58, v59
	ds_write_b32 v110, v58 offset:8384
	v_bfe_u32 v58, v60, 17, 1
	v_add3_u32 v58, v60, v58, s86
	v_bfe_u32 v59, v64, 17, 1
	v_and_b32_e32 v58, 0xfffe0000, v58
	v_add3_u32 v59, v64, v59, s86
	v_and_b32_e32 v59, 0xfffe0000, v59
	v_cvt_pk_bf16_f32 v58, v58, v59
	ds_write_b32 v110, v58 offset:8512
	v_bfe_u32 v58, v61, 17, 1
	v_add3_u32 v58, v61, v58, s86
	v_bfe_u32 v59, v65, 17, 1
	v_and_b32_e32 v58, 0xfffe0000, v58
	v_add3_u32 v59, v65, v59, s86
	v_and_b32_e32 v59, 0xfffe0000, v59
	v_cvt_pk_bf16_f32 v58, v58, v59
	ds_write_b32 v110, v58 offset:8640
	s_waitcnt vmcnt(13)
	v_bfe_u32 v58, v50, 17, 1
	v_add3_u32 v50, v50, v58, s86
	s_waitcnt vmcnt(12)
	v_bfe_u32 v58, v54, 17, 1
	v_and_b32_e32 v50, 0xfffe0000, v50
	v_add3_u32 v54, v54, v58, s86
	v_and_b32_e32 v54, 0xfffe0000, v54
	v_cvt_pk_bf16_f32 v50, v50, v54
	ds_write_b32 v110, v50 offset:9288
	v_bfe_u32 v50, v51, 17, 1
	v_add3_u32 v50, v51, v50, s86
	v_bfe_u32 v51, v55, 17, 1
	v_and_b32_e32 v50, 0xfffe0000, v50
	v_add3_u32 v51, v55, v51, s86
	v_and_b32_e32 v51, 0xfffe0000, v51
	v_cvt_pk_bf16_f32 v50, v50, v51
	ds_write_b32 v110, v50 offset:9416
	v_bfe_u32 v50, v52, 17, 1
	v_add3_u32 v50, v52, v50, s86
	v_bfe_u32 v51, v56, 17, 1
	v_and_b32_e32 v50, 0xfffe0000, v50
	v_add3_u32 v51, v56, v51, s86
	v_and_b32_e32 v51, 0xfffe0000, v51
	v_cvt_pk_bf16_f32 v50, v50, v51
	ds_write_b32 v110, v50 offset:9544
	v_bfe_u32 v50, v53, 17, 1
	v_add3_u32 v50, v53, v50, s86
	v_bfe_u32 v51, v57, 17, 1
	v_and_b32_e32 v50, 0xfffe0000, v50
	v_add3_u32 v51, v57, v51, s86
	v_and_b32_e32 v51, 0xfffe0000, v51
	v_cvt_pk_bf16_f32 v50, v50, v51
	ds_write_b32 v110, v50 offset:9672
	s_waitcnt vmcnt(11)
	v_bfe_u32 v50, v42, 17, 1
	v_add3_u32 v42, v42, v50, s86
	s_waitcnt vmcnt(10)
	v_bfe_u32 v50, v46, 17, 1
	v_and_b32_e32 v42, 0xfffe0000, v42
	v_add3_u32 v46, v46, v50, s86
	v_and_b32_e32 v46, 0xfffe0000, v46
	v_cvt_pk_bf16_f32 v42, v42, v46
	ds_write_b32 v110, v42 offset:10320
	v_bfe_u32 v42, v43, 17, 1
	v_add3_u32 v42, v43, v42, s86
	v_bfe_u32 v43, v47, 17, 1
	v_and_b32_e32 v42, 0xfffe0000, v42
	v_add3_u32 v43, v47, v43, s86
	v_and_b32_e32 v43, 0xfffe0000, v43
	v_cvt_pk_bf16_f32 v42, v42, v43
	ds_write_b32 v110, v42 offset:10448
	v_bfe_u32 v42, v44, 17, 1
	v_add3_u32 v42, v44, v42, s86
	v_bfe_u32 v43, v48, 17, 1
	v_and_b32_e32 v42, 0xfffe0000, v42
	v_add3_u32 v43, v48, v43, s86
	v_and_b32_e32 v43, 0xfffe0000, v43
	v_cvt_pk_bf16_f32 v42, v42, v43
	ds_write_b32 v110, v42 offset:10576
	v_bfe_u32 v42, v45, 17, 1
	v_add3_u32 v42, v45, v42, s86
	v_bfe_u32 v43, v49, 17, 1
	v_and_b32_e32 v42, 0xfffe0000, v42
	v_add3_u32 v43, v49, v43, s86
	v_and_b32_e32 v43, 0xfffe0000, v43
	v_cvt_pk_bf16_f32 v42, v42, v43
	ds_write_b32 v110, v42 offset:10704
	s_waitcnt vmcnt(9)
	v_bfe_u32 v42, v34, 17, 1
	v_add3_u32 v34, v34, v42, s86
	s_waitcnt vmcnt(8)
	v_bfe_u32 v42, v38, 17, 1
	v_and_b32_e32 v34, 0xfffe0000, v34
	v_add3_u32 v38, v38, v42, s86
	v_and_b32_e32 v38, 0xfffe0000, v38
	v_cvt_pk_bf16_f32 v34, v34, v38
	ds_write_b32 v110, v34 offset:11352
	v_bfe_u32 v34, v35, 17, 1
	v_add3_u32 v34, v35, v34, s86
	v_bfe_u32 v35, v39, 17, 1
	v_and_b32_e32 v34, 0xfffe0000, v34
	v_add3_u32 v35, v39, v35, s86
	v_and_b32_e32 v35, 0xfffe0000, v35
	v_cvt_pk_bf16_f32 v34, v34, v35
	ds_write_b32 v110, v34 offset:11480
	v_bfe_u32 v34, v36, 17, 1
	v_add3_u32 v34, v36, v34, s86
	v_bfe_u32 v35, v40, 17, 1
	v_and_b32_e32 v34, 0xfffe0000, v34
	v_add3_u32 v35, v40, v35, s86
	v_and_b32_e32 v35, 0xfffe0000, v35
	v_cvt_pk_bf16_f32 v34, v34, v35
	ds_write_b32 v110, v34 offset:11608
	v_bfe_u32 v34, v37, 17, 1
	v_add3_u32 v34, v37, v34, s86
	v_bfe_u32 v35, v41, 17, 1
	v_and_b32_e32 v34, 0xfffe0000, v34
	v_add3_u32 v35, v41, v35, s86
	v_and_b32_e32 v35, 0xfffe0000, v35
	v_cvt_pk_bf16_f32 v34, v34, v35
	ds_write_b32 v110, v34 offset:11736
	s_waitcnt vmcnt(7)
	v_bfe_u32 v34, v26, 17, 1
	v_add3_u32 v26, v26, v34, s86
	s_waitcnt vmcnt(6)
	v_bfe_u32 v34, v30, 17, 1
	v_and_b32_e32 v26, 0xfffe0000, v26
	v_add3_u32 v30, v30, v34, s86
	v_and_b32_e32 v30, 0xfffe0000, v30
	v_cvt_pk_bf16_f32 v26, v26, v30
	ds_write_b32 v110, v26 offset:12384
	v_bfe_u32 v26, v27, 17, 1
	v_add3_u32 v26, v27, v26, s86
	v_bfe_u32 v27, v31, 17, 1
	v_and_b32_e32 v26, 0xfffe0000, v26
	v_add3_u32 v27, v31, v27, s86
	v_and_b32_e32 v27, 0xfffe0000, v27
	v_cvt_pk_bf16_f32 v26, v26, v27
	ds_write_b32 v110, v26 offset:12512
	v_bfe_u32 v26, v28, 17, 1
	v_add3_u32 v26, v28, v26, s86
	v_bfe_u32 v27, v32, 17, 1
	v_and_b32_e32 v26, 0xfffe0000, v26
	v_add3_u32 v27, v32, v27, s86
	v_and_b32_e32 v27, 0xfffe0000, v27
	v_cvt_pk_bf16_f32 v26, v26, v27
	ds_write_b32 v110, v26 offset:12640
	v_bfe_u32 v26, v29, 17, 1
	v_add3_u32 v26, v29, v26, s86
	v_bfe_u32 v27, v33, 17, 1
	v_and_b32_e32 v26, 0xfffe0000, v26
	v_add3_u32 v27, v33, v27, s86
	v_and_b32_e32 v27, 0xfffe0000, v27
	v_cvt_pk_bf16_f32 v26, v26, v27
	ds_write_b32 v110, v26 offset:12768
	s_waitcnt vmcnt(5)
	v_bfe_u32 v26, v18, 17, 1
	v_add3_u32 v18, v18, v26, s86
	s_waitcnt vmcnt(4)
	v_bfe_u32 v26, v22, 17, 1
	v_and_b32_e32 v18, 0xfffe0000, v18
	v_add3_u32 v22, v22, v26, s86
	v_and_b32_e32 v22, 0xfffe0000, v22
	v_cvt_pk_bf16_f32 v18, v18, v22
	ds_write_b32 v110, v18 offset:13416
	v_bfe_u32 v18, v19, 17, 1
	v_add3_u32 v18, v19, v18, s86
	v_bfe_u32 v19, v23, 17, 1
	v_and_b32_e32 v18, 0xfffe0000, v18
	v_add3_u32 v19, v23, v19, s86
	v_and_b32_e32 v19, 0xfffe0000, v19
	v_cvt_pk_bf16_f32 v18, v18, v19
	ds_write_b32 v110, v18 offset:13544
	v_bfe_u32 v18, v20, 17, 1
	v_add3_u32 v18, v20, v18, s86
	v_bfe_u32 v19, v24, 17, 1
	v_and_b32_e32 v18, 0xfffe0000, v18
	v_add3_u32 v19, v24, v19, s86
	v_and_b32_e32 v19, 0xfffe0000, v19
	v_cvt_pk_bf16_f32 v18, v18, v19
	ds_write_b32 v110, v18 offset:13672
	v_bfe_u32 v18, v21, 17, 1
	v_add3_u32 v18, v21, v18, s86
	v_bfe_u32 v19, v25, 17, 1
	v_and_b32_e32 v18, 0xfffe0000, v18
	v_add3_u32 v19, v25, v19, s86
	v_and_b32_e32 v19, 0xfffe0000, v19
	v_cvt_pk_bf16_f32 v18, v18, v19
	ds_write_b32 v110, v18 offset:13800
	s_waitcnt vmcnt(3)
	v_bfe_u32 v18, v10, 17, 1
	v_add3_u32 v10, v10, v18, s86
	s_waitcnt vmcnt(2)
	v_bfe_u32 v18, v14, 17, 1
	v_and_b32_e32 v10, 0xfffe0000, v10
	v_add3_u32 v14, v14, v18, s86
	v_and_b32_e32 v14, 0xfffe0000, v14
	v_cvt_pk_bf16_f32 v10, v10, v14
	ds_write_b32 v110, v10 offset:14448
	v_bfe_u32 v10, v11, 17, 1
	v_add3_u32 v10, v11, v10, s86
	v_bfe_u32 v11, v15, 17, 1
	v_and_b32_e32 v10, 0xfffe0000, v10
	v_add3_u32 v11, v15, v11, s86
	v_and_b32_e32 v11, 0xfffe0000, v11
	v_cvt_pk_bf16_f32 v10, v10, v11
	ds_write_b32 v110, v10 offset:14576
	v_bfe_u32 v10, v12, 17, 1
	v_add3_u32 v10, v12, v10, s86
	v_bfe_u32 v11, v16, 17, 1
	v_and_b32_e32 v10, 0xfffe0000, v10
	v_add3_u32 v11, v16, v11, s86
	v_and_b32_e32 v11, 0xfffe0000, v11
	v_cvt_pk_bf16_f32 v10, v10, v11
	ds_write_b32 v110, v10 offset:14704
	v_bfe_u32 v10, v13, 17, 1
	v_add3_u32 v10, v13, v10, s86
	v_bfe_u32 v11, v17, 17, 1
	v_and_b32_e32 v10, 0xfffe0000, v10
	v_add3_u32 v11, v17, v11, s86
	v_and_b32_e32 v11, 0xfffe0000, v11
	v_cvt_pk_bf16_f32 v10, v10, v11
	ds_write_b32 v110, v10 offset:14832
	s_waitcnt vmcnt(1)
	v_bfe_u32 v10, v2, 17, 1
	v_add3_u32 v2, v2, v10, s86
	s_waitcnt vmcnt(0)
	v_bfe_u32 v10, v6, 17, 1
	v_and_b32_e32 v2, 0xfffe0000, v2
	v_add3_u32 v6, v6, v10, s86
	v_and_b32_e32 v6, 0xfffe0000, v6
	v_cvt_pk_bf16_f32 v2, v2, v6
	ds_write_b32 v110, v2 offset:15480
	v_bfe_u32 v2, v3, 17, 1
	v_add3_u32 v2, v3, v2, s86
	v_bfe_u32 v3, v7, 17, 1
	v_and_b32_e32 v2, 0xfffe0000, v2
	v_add3_u32 v3, v7, v3, s86
	v_and_b32_e32 v3, 0xfffe0000, v3
	v_cvt_pk_bf16_f32 v2, v2, v3
	ds_write_b32 v110, v2 offset:15608
	v_bfe_u32 v2, v4, 17, 1
	v_add3_u32 v2, v4, v2, s86
	v_bfe_u32 v3, v8, 17, 1
	v_and_b32_e32 v2, 0xfffe0000, v2
	v_add3_u32 v3, v8, v3, s86
	v_and_b32_e32 v3, 0xfffe0000, v3
	v_cvt_pk_bf16_f32 v2, v2, v3
	ds_write_b32 v110, v2 offset:15736
	v_bfe_u32 v2, v5, 17, 1
	v_add3_u32 v2, v5, v2, s86
	v_bfe_u32 v3, v9, 17, 1
	v_and_b32_e32 v2, 0xfffe0000, v2
	v_add3_u32 v3, v9, v3, s86
	v_and_b32_e32 v3, 0xfffe0000, v3
	v_cvt_pk_bf16_f32 v2, v2, v3
	ds_write_b32 v110, v2 offset:15864
	s_waitcnt lgkmcnt(0)
	ds_read2_b32 v[20:21], v146 offset1:8
	ds_read2_b32 v[4:5], v146 offset0:129 offset1:137
	v_add_u32_e32 v30, 0x400, v146
	ds_read2_b32 v[22:23], v30 offset0:2 offset1:10
	ds_read2_b32 v[6:7], v30 offset0:131 offset1:139
	v_add_u32_e32 v32, 0x400, v147
	ds_read2_b32 v[24:25], v147 offset1:8
	ds_read2_b32 v[12:13], v147 offset0:129 offset1:137
	ds_read2_b32 v[26:27], v32 offset0:2 offset1:10
	ds_read2_b32 v[14:15], v32 offset0:131 offset1:139
	v_or_b32_e32 v31, s2, v131
	v_lshl_add_u64 v[2:3], s[40:41], 0, v[132:133]
	s_waitcnt lgkmcnt(6)
	v_mov_b32_e32 v9, v4
	v_or3_b32 v4, v31, v145, s4
	v_or_b32_e32 v33, s2, v144
	v_lshl_add_u64 v[2:3], v[2:3], 0, s[44:45]
	v_lshlrev_b32_e32 v132, 7, v4
	v_or3_b32 v4, v33, v145, s4
	v_mov_b32_e32 v8, v20
	s_waitcnt lgkmcnt(5)
	v_mov_b32_e32 v10, v22
	s_waitcnt lgkmcnt(4)
	v_mov_b32_e32 v11, v6
	v_lshl_add_u64 v[16:17], v[2:3], 0, v[132:133]
	v_lshlrev_b32_e32 v132, 7, v4
	global_store_dwordx4 v[16:17], v[8:11], off
	v_lshl_add_u64 v[16:17], v[2:3], 0, v[132:133]
	v_add_u32_e32 v4, 0x400, v149
	s_waitcnt lgkmcnt(3)
	v_mov_b32_e32 v8, v24
	s_waitcnt lgkmcnt(2)
	v_mov_b32_e32 v9, v12
	s_waitcnt lgkmcnt(1)
	v_mov_b32_e32 v10, v26
	s_waitcnt lgkmcnt(0)
	v_mov_b32_e32 v11, v14
	global_store_dwordx4 v[16:17], v[8:11], off
	ds_read2_b32 v[10:11], v4 offset0:2 offset1:131
	v_or3_b32 v4, v31, v148, s4
	ds_read2_b32 v[8:9], v149 offset1:129
	v_lshlrev_b32_e32 v132, 7, v4
	v_add_u32_e32 v4, 0x400, v150
	ds_read2_b32 v[16:17], v150 offset1:129
	ds_read2_b32 v[18:19], v4 offset0:2 offset1:131
	v_or3_b32 v4, v33, v148, s4
	v_lshl_add_u64 v[28:29], v[2:3], 0, v[132:133]
	v_lshlrev_b32_e32 v132, 7, v4
	s_waitcnt lgkmcnt(2)
	global_store_dwordx4 v[28:29], v[8:11], off
	v_mov_b32_e32 v4, v21
	v_mov_b32_e32 v6, v23
	v_lshl_add_u64 v[8:9], v[2:3], 0, v[132:133]
	s_waitcnt lgkmcnt(0)
	global_store_dwordx4 v[8:9], v[16:19], off
	v_or3_b32 v8, v31, v151, s4
	v_lshlrev_b32_e32 v132, 7, v8
	v_lshl_add_u64 v[8:9], v[2:3], 0, v[132:133]
	global_store_dwordx4 v[8:9], v[4:7], off
	v_mov_b32_e32 v12, v25
	v_mov_b32_e32 v14, v27
	v_or3_b32 v4, v33, v151, s4
	v_add_u32_e32 v6, 0x400, v153
	v_lshlrev_b32_e32 v132, 7, v4
	ds_read2_b32 v[4:5], v153 offset1:129
	ds_read2_b32 v[6:7], v6 offset0:2 offset1:131
	v_lshl_add_u64 v[8:9], v[2:3], 0, v[132:133]
	global_store_dwordx4 v[8:9], v[12:15], off
	v_or3_b32 v8, v31, v152, s4
	v_lshlrev_b32_e32 v132, 7, v8
	v_lshl_add_u64 v[8:9], v[2:3], 0, v[132:133]
	s_waitcnt lgkmcnt(0)
	global_store_dwordx4 v[8:9], v[4:7], off
	ds_read2_b32 v[4:5], v154 offset1:129
	v_or3_b32 v8, v33, v152, s4
	v_add_u32_e32 v6, 0x400, v154
	ds_read2_b32 v[6:7], v6 offset0:2 offset1:131
	v_lshlrev_b32_e32 v132, 7, v8
	v_lshl_add_u64 v[12:13], v[2:3], 0, v[132:133]
	ds_read2_b32 v[20:21], v146 offset0:16 offset1:24
	ds_read2_b32 v[8:9], v146 offset0:145 offset1:153
	ds_read2_b32 v[22:23], v30 offset0:18 offset1:26
	ds_read2_b32 v[10:11], v30 offset0:147 offset1:155
	s_waitcnt lgkmcnt(4)
	global_store_dwordx4 v[12:13], v[4:7], off
	ds_read2_b32 v[24:25], v147 offset0:16 offset1:24
	ds_read2_b32 v[12:13], v147 offset0:145 offset1:153
	ds_read2_b32 v[26:27], v32 offset0:18 offset1:26
	ds_read2_b32 v[14:15], v32 offset0:147 offset1:155
	s_waitcnt lgkmcnt(6)
	v_mov_b32_e32 v5, v8
	v_or3_b32 v8, v31, v155, s4
	v_lshlrev_b32_e32 v132, 7, v8
	v_or3_b32 v8, v33, v155, s4
	v_mov_b32_e32 v4, v20
	s_waitcnt lgkmcnt(5)
	v_mov_b32_e32 v6, v22
	s_waitcnt lgkmcnt(4)
	v_mov_b32_e32 v7, v10
	v_lshl_add_u64 v[16:17], v[2:3], 0, v[132:133]
	v_lshlrev_b32_e32 v132, 7, v8
	global_store_dwordx4 v[16:17], v[4:7], off
	v_lshl_add_u64 v[16:17], v[2:3], 0, v[132:133]
	v_or3_b32 v8, v31, v158, s4
	s_waitcnt lgkmcnt(3)
	v_mov_b32_e32 v4, v24
	s_waitcnt lgkmcnt(2)
	v_mov_b32_e32 v5, v12
	s_waitcnt lgkmcnt(1)
	v_mov_b32_e32 v6, v26
	s_waitcnt lgkmcnt(0)
	v_mov_b32_e32 v7, v14
	global_store_dwordx4 v[16:17], v[4:7], off
	ds_read2_b32 v[4:5], v159 offset1:129
	v_lshlrev_b32_e32 v132, 7, v8
	v_add_u32_e32 v6, 0x400, v159
	ds_read2_b32 v[6:7], v6 offset0:2 offset1:131
	v_add_u32_e32 v8, 0x400, v160
	ds_read2_b32 v[16:17], v160 offset1:129
	ds_read2_b32 v[18:19], v8 offset0:2 offset1:131
	v_lshl_add_u64 v[28:29], v[2:3], 0, v[132:133]
	s_waitcnt lgkmcnt(2)
	global_store_dwordx4 v[28:29], v[4:7], off
	v_mov_b32_e32 v8, v21
	v_mov_b32_e32 v10, v23
	v_or3_b32 v4, v33, v158, s4
	v_lshlrev_b32_e32 v132, 7, v4
	v_lshl_add_u64 v[4:5], v[2:3], 0, v[132:133]
	s_waitcnt lgkmcnt(0)
	global_store_dwordx4 v[4:5], v[16:19], off
	v_or3_b32 v4, v31, v161, s4
	v_lshlrev_b32_e32 v132, 7, v4
	v_lshl_add_u64 v[4:5], v[2:3], 0, v[132:133]
	global_store_dwordx4 v[4:5], v[8:11], off
	v_or3_b32 v4, v33, v161, s4
	v_lshlrev_b32_e32 v132, 7, v4
	v_mov_b32_e32 v12, v25
	v_mov_b32_e32 v14, v27
	v_lshl_add_u64 v[4:5], v[2:3], 0, v[132:133]
	v_add_u32_e32 v6, 0x400, v163
	global_store_dwordx4 v[4:5], v[12:15], off
	ds_read2_b32 v[4:5], v163 offset1:129
	ds_read2_b32 v[6:7], v6 offset0:2 offset1:131
	v_or3_b32 v8, v31, v162, s4
	v_add_u32_e32 v10, 0x400, v164
	v_lshlrev_b32_e32 v132, 7, v8
	ds_read2_b32 v[8:9], v164 offset1:129
	ds_read2_b32 v[10:11], v10 offset0:2 offset1:131
	v_lshl_add_u64 v[12:13], v[2:3], 0, v[132:133]
	s_waitcnt lgkmcnt(2)
	global_store_dwordx4 v[12:13], v[4:7], off
	s_nop 1
	v_or3_b32 v4, v33, v162, s4
	v_lshlrev_b32_e32 v132, 7, v4
	v_lshl_add_u64 v[2:3], v[2:3], 0, v[132:133]
	s_waitcnt lgkmcnt(0)
	global_store_dwordx4 v[2:3], v[8:11], off
	s_waitcnt lgkmcnt(0)

.LBB0_26:
	s_andn2_b64 vcc, exec, s[4:5]
	s_cbranch_vccnz .LBB0_60
	s_mul_i32 s4, s42, 0x1c00000
	s_mul_hi_i32 s2, s42, 0x1c00000
	s_add_u32 s4, s6, s4
	s_addc_u32 s5, s7, s2
	s_lshl_b32 s44, s42, 11
	s_ashr_i32 s45, s44, 31
	s_lshl_b64 s[44:45], s[44:45], 2
	s_add_u32 s44, s26, s44
	s_addc_u32 s45, s27, s45
	s_add_i32 s2, s70, 0xea00
	s_bfe_u32 s38, s2, 0xe0002
	s_mulk_i32 s38, 0x4925
	s_lshr_b32 s71, s38, 17
	s_mul_i32 s38, s71, 28
	s_sub_i32 s38, s2, s38
	s_and_b32 vcc_lo, s38, 0xffff
	s_lshl_b32 s43, vcc_lo, 7
	s_bfe_u32 s38, s38, 0xf0001
	s_lshl_b32 vcc_lo, vcc_lo, 9
	s_add_i32 vcc_hi, s38, -10
	s_and_b32 vcc_lo, vcc_lo, 0x200
	s_lshl_b32 s38, s38, 7
	s_add_i32 s38, s38, vcc_lo
	s_lshl_b32 s2, s71, 6
	s_addk_i32 s38, 0x300
	s_cmp_lt_u32 vcc_hi, -4
	s_cselect_b32 s38, s43, s38
	v_or_b32_e32 v137, s2, v165
	v_mov_b64_e32 v[2:3], s[4:5]
	s_movk_i32 s4, 0x3800
	v_mad_u64_u32 v[2:3], s[4:5], v137, s4, v[2:3]
	s_lshl_b32 s38, s38, 2
	v_lshl_add_u64 v[2:3], v[2:3], 0, s[38:39]
	v_lshlrev_b32_e32 v132, 2, v130
	v_lshl_add_u64 v[2:3], v[2:3], 0, v[132:133]
	s_movk_i32 s4, 0x3000
	v_add_co_u32_e32 v4, vcc, s4, v2
	s_mov_b32 s4, 0xe000
	s_nop 0
	v_addc_co_u32_e32 v5, vcc, 0, v3, vcc
	global_load_dwordx4 v[126:129], v[2:3], off nt
	global_load_dwordx4 v[122:125], v[4:5], off offset:2048 nt
	v_add_co_u32_e32 v4, vcc, s4, v2
	s_mov_b32 s4, 0x11000
	s_nop 0
	v_addc_co_u32_e32 v5, vcc, 0, v3, vcc
	v_add_co_u32_e32 v6, vcc, s4, v2
	s_mov_b32 s4, 0x1c000
	s_nop 0
	v_addc_co_u32_e32 v7, vcc, 0, v3, vcc
	global_load_dwordx4 v[118:121], v[4:5], off nt
	global_load_dwordx4 v[114:117], v[6:7], off offset:2048 nt
	v_add_co_u32_e32 v4, vcc, s4, v2
	s_mov_b32 s4, 0x1f000
	s_nop 0
	v_addc_co_u32_e32 v5, vcc, 0, v3, vcc
	v_add_co_u32_e32 v6, vcc, s4, v2
	s_mov_b32 s4, 0x2d000
	s_nop 0
	v_addc_co_u32_e32 v7, vcc, 0, v3, vcc
	global_load_dwordx4 v[110:113], v[4:5], off nt
	global_load_dwordx4 v[106:109], v[6:7], off offset:2048 nt
	v_add_co_u32_e32 v4, vcc, s58, v2
	v_cndmask_b32_e64 v132, 0, 1, s[0:1]
	s_nop 0
	v_addc_co_u32_e32 v5, vcc, 0, v3, vcc
	v_add_co_u32_e32 v6, vcc, s4, v2
	s_mov_b32 s4, 0x3b000
	s_nop 0
	v_addc_co_u32_e32 v7, vcc, 0, v3, vcc
	global_load_dwordx4 v[102:105], v[4:5], off nt
	global_load_dwordx4 v[98:101], v[6:7], off offset:2048 nt
	v_add_co_u32_e32 v4, vcc, s61, v2
	v_mov_b32_e32 v136, 1.0
	s_nop 0
	v_addc_co_u32_e32 v5, vcc, 0, v3, vcc
	v_add_co_u32_e32 v6, vcc, s4, v2
	s_mov_b32 s4, 0x46000
	s_nop 0
	v_addc_co_u32_e32 v7, vcc, 0, v3, vcc
	global_load_dwordx4 v[94:97], v[4:5], off nt
	global_load_dwordx4 v[90:93], v[6:7], off offset:2048 nt
	v_add_co_u32_e32 v4, vcc, s4, v2
	s_mov_b32 s4, 0x49000
	s_nop 0
	v_addc_co_u32_e32 v5, vcc, 0, v3, vcc
	v_add_co_u32_e32 v6, vcc, s4, v2
	s_mov_b32 s4, 0x54000
	s_nop 0
	v_addc_co_u32_e32 v7, vcc, 0, v3, vcc
	global_load_dwordx4 v[86:89], v[4:5], off nt
	global_load_dwordx4 v[82:85], v[6:7], off offset:2048 nt
	v_add_co_u32_e32 v4, vcc, s4, v2
	s_mov_b32 s4, 0x57000
	s_nop 0
	v_addc_co_u32_e32 v5, vcc, 0, v3, vcc
	v_add_co_u32_e32 v6, vcc, s4, v2
	s_mov_b32 s4, 0x65000
	s_nop 0
	v_addc_co_u32_e32 v7, vcc, 0, v3, vcc
	global_load_dwordx4 v[78:81], v[4:5], off nt
	global_load_dwordx4 v[74:77], v[6:7], off offset:2048 nt
	v_add_co_u32_e32 v4, vcc, s79, v2
	v_mov_b32_e32 v138, 1.0
	s_nop 0
	v_addc_co_u32_e32 v5, vcc, 0, v3, vcc
	v_add_co_u32_e32 v6, vcc, s4, v2
	s_mov_b32 s4, 0x73000
	s_nop 0
	v_addc_co_u32_e32 v7, vcc, 0, v3, vcc
	global_load_dwordx4 v[70:73], v[4:5], off nt
	global_load_dwordx4 v[66:69], v[6:7], off offset:2048 nt
	v_add_co_u32_e32 v4, vcc, s82, v2
	v_mov_b32_e32 v139, 1.0
	s_nop 0
	v_addc_co_u32_e32 v5, vcc, 0, v3, vcc
	v_add_co_u32_e32 v6, vcc, s4, v2
	s_mov_b32 s4, 0x7e000
	s_nop 0
	v_addc_co_u32_e32 v7, vcc, 0, v3, vcc
	global_load_dwordx4 v[62:65], v[4:5], off nt
	global_load_dwordx4 v[58:61], v[6:7], off offset:2048 nt
	v_add_co_u32_e32 v4, vcc, s4, v2
	s_mov_b32 s4, 0x81000
	s_nop 0
	v_addc_co_u32_e32 v5, vcc, 0, v3, vcc
	v_add_co_u32_e32 v6, vcc, s4, v2
	s_mov_b32 s4, 0x8c000
	s_nop 0
	v_addc_co_u32_e32 v7, vcc, 0, v3, vcc
	global_load_dwordx4 v[54:57], v[4:5], off nt
	global_load_dwordx4 v[50:53], v[6:7], off offset:2048 nt
	v_add_co_u32_e32 v4, vcc, s4, v2
	s_mov_b32 s4, 0x9a000
	s_nop 0
	v_addc_co_u32_e32 v5, vcc, 0, v3, vcc
	v_add_co_u32_e32 v6, vcc, s87, v2
	s_nop 1
	v_addc_co_u32_e32 v7, vcc, 0, v3, vcc
	global_load_dwordx4 v[46:49], v[4:5], off nt
	global_load_dwordx4 v[42:45], v[6:7], off offset:2048 nt
	v_add_co_u32_e32 v4, vcc, s4, v2
	s_mov_b32 s4, 0x9d000
	s_nop 0
	v_addc_co_u32_e32 v5, vcc, 0, v3, vcc
	v_add_co_u32_e32 v6, vcc, s4, v2
	s_mov_b32 s4, 0xa8000
	s_nop 0
	v_addc_co_u32_e32 v7, vcc, 0, v3, vcc
	global_load_dwordx4 v[38:41], v[4:5], off nt
	global_load_dwordx4 v[34:37], v[6:7], off offset:2048 nt
	v_add_co_u32_e32 v4, vcc, s4, v2
	s_mov_b32 s4, 0xab000
	s_nop 0
	v_addc_co_u32_e32 v5, vcc, 0, v3, vcc
	v_add_co_u32_e32 v6, vcc, s4, v2
	s_mov_b32 s4, 0xb6000
	s_nop 0
	v_addc_co_u32_e32 v7, vcc, 0, v3, vcc
	global_load_dwordx4 v[30:33], v[4:5], off nt
	global_load_dwordx4 v[26:29], v[6:7], off offset:2048 nt
	v_add_co_u32_e32 v4, vcc, s4, v2
	s_mov_b32 s4, 0xb9000
	s_nop 0
	v_addc_co_u32_e32 v5, vcc, 0, v3, vcc
	v_add_co_u32_e32 v6, vcc, s4, v2
	s_mov_b32 s4, 0xc4000
	s_nop 0
	v_addc_co_u32_e32 v7, vcc, 0, v3, vcc
	global_load_dwordx4 v[22:25], v[4:5], off nt
	global_load_dwordx4 v[18:21], v[6:7], off offset:2048 nt
	v_add_co_u32_e32 v4, vcc, s4, v2
	v_cmp_ne_u32_e64 s[4:5], 1, v132
	s_nop 0
	v_addc_co_u32_e32 v5, vcc, 0, v3, vcc
	v_add_co_u32_e32 v6, vcc, 0xc7000, v2
	s_nop 1
	v_addc_co_u32_e32 v7, vcc, 0, v3, vcc
	global_load_dwordx4 v[14:17], v[4:5], off nt
	global_load_dwordx4 v[10:13], v[6:7], off offset:2048 nt
	v_add_co_u32_e32 v4, vcc, 0xd2000, v2
	s_nop 1
	v_addc_co_u32_e32 v5, vcc, 0, v3, vcc
	v_add_co_u32_e32 v2, vcc, 0xd5000, v2
	s_nop 1
	v_addc_co_u32_e32 v3, vcc, 0, v3, vcc
	global_load_dwordx4 v[6:9], v[4:5], off nt
	s_nop 0
	global_load_dwordx4 v[2:5], v[2:3], off offset:2048 nt
	s_andn2_b64 vcc, exec, s[0:1]
	s_cbranch_vccnz .LBB0_29
	v_lshlrev_b32_e32 v132, 2, v137
	global_load_dwordx2 v[138:139], v132, s[44:45]
	v_or_b32_e32 v228, s2, v166
	v_lshlrev_b32_e32 v228, 2, v228
	global_load_dwordx2 v[192:193], v228, s[44:45]
	v_or_b32_e32 v228, s2, v167
	v_lshlrev_b32_e32 v228, 2, v228
	global_load_dwordx2 v[194:195], v228, s[44:45]
	v_or_b32_e32 v228, s2, v169
	v_lshlrev_b32_e32 v228, 2, v228
	global_load_dwordx2 v[196:197], v228, s[44:45]
	v_or_b32_e32 v228, s2, v171
	v_lshlrev_b32_e32 v228, 2, v228
	global_load_dwordx2 v[198:199], v228, s[44:45]
	v_or_b32_e32 v228, s2, v173
	v_lshlrev_b32_e32 v228, 2, v228
	global_load_dwordx2 v[200:201], v228, s[44:45]
	v_or_b32_e32 v228, s2, v175
	v_lshlrev_b32_e32 v228, 2, v228
	global_load_dwordx2 v[202:203], v228, s[44:45]
	v_or_b32_e32 v228, s2, v177
	v_lshlrev_b32_e32 v228, 2, v228
	global_load_dwordx2 v[204:205], v228, s[44:45]
	v_or_b32_e32 v228, s2, v179
	v_lshlrev_b32_e32 v228, 2, v228
	global_load_dwordx2 v[206:207], v228, s[44:45]
	v_or_b32_e32 v228, s2, v181
	v_lshlrev_b32_e32 v228, 2, v228
	global_load_dwordx2 v[208:209], v228, s[44:45]
	v_or_b32_e32 v228, s2, v183
	v_lshlrev_b32_e32 v228, 2, v228
	global_load_dwordx2 v[210:211], v228, s[44:45]
	v_or_b32_e32 v228, s2, v185
	v_lshlrev_b32_e32 v228, 2, v228
	global_load_dwordx2 v[212:213], v228, s[44:45]
	v_or_b32_e32 v228, s2, v187
	v_lshlrev_b32_e32 v228, 2, v228
	global_load_dwordx2 v[214:215], v228, s[44:45]
	v_or_b32_e32 v228, s2, v188
	v_lshlrev_b32_e32 v228, 2, v228
	global_load_dwordx2 v[216:217], v228, s[44:45]
	v_or_b32_e32 v228, s2, v189
	v_lshlrev_b32_e32 v228, 2, v228
	global_load_dwordx2 v[218:219], v228, s[44:45]
	v_or_b32_e32 v228, s2, v190
	v_lshlrev_b32_e32 v228, 2, v228
	global_load_dwordx2 v[230:231], v228, s[44:45]

.LBB0_61:
	s_andn2_b64 vcc, exec, s[4:5]
	s_cbranch_vccnz .LBB0_95
	s_mul_i32 s4, s42, 0x5800000
	s_mul_hi_i32 s2, s42, 0x5800000
	s_add_u32 s4, s20, s4
	s_addc_u32 s5, s21, s2
	s_lshl_b32 s44, s42, 11
	s_ashr_i32 s45, s44, 31
	s_lshl_b64 s[44:45], s[44:45], 2
	s_add_u32 s44, s18, s44
	s_addc_u32 s45, s19, s45
	s_add_i32 s2, s70, 0xf500
	s_and_b32 s38, s2, 0xffff
	s_mul_i32 s38, s38, 0xba2f
	s_lshr_b32 s43, s38, 22
	s_mul_i32 s71, s43, 0x58
	s_lshr_b32 s38, s38, 16
	s_sub_i32 vcc_lo, s2, s71
	s_and_b32 s2, vcc_lo, 0xffff
	s_and_b32 s71, s38, 0xffc0
	s_bitcmp0_b32 vcc_lo, 0
	s_cselect_b32 s38, 0, 0x1600
	s_lshl_b32 vcc_lo, s2, 6
	s_and_b32 vcc_lo, vcc_lo, 0x1f80
	s_add_i32 s38, s38, vcc_lo
	v_or_b32_e32 v137, s71, v165
	v_mov_b64_e32 v[2:3], s[4:5]
	v_mad_u64_u32 v[2:3], s[4:5], v137, s88, v[2:3]
	s_lshl_b32 s38, s38, 2
	v_lshl_add_u64 v[2:3], v[2:3], 0, s[38:39]
	v_lshlrev_b32_e32 v132, 2, v130
	v_lshl_add_u64 v[2:3], v[2:3], 0, v[132:133]
	v_add_co_u32_e32 v4, vcc, s88, v2
	v_cndmask_b32_e64 v132, 0, 1, s[34:35]
	s_nop 0
	v_addc_co_u32_e32 v5, vcc, 0, v3, vcc
	global_load_dwordx4 v[126:129], v[2:3], off nt
	global_load_dwordx4 v[122:125], v[4:5], off nt
	v_add_co_u32_e32 v4, vcc, s89, v2
	v_mov_b32_e32 v136, 1.0
	s_nop 0
	v_addc_co_u32_e32 v5, vcc, 0, v3, vcc
	v_add_co_u32_e32 v6, vcc, s90, v2
	v_cmp_ne_u32_e64 s[4:5], 1, v132
	s_nop 0
	v_addc_co_u32_e32 v7, vcc, 0, v3, vcc
	global_load_dwordx4 v[118:121], v[4:5], off nt
	global_load_dwordx4 v[114:117], v[6:7], off nt
	v_add_co_u32_e32 v4, vcc, s76, v2
	v_mov_b32_e32 v138, 1.0
	s_nop 0
	v_addc_co_u32_e32 v5, vcc, 0, v3, vcc
	v_add_co_u32_e32 v6, vcc, s91, v2
	v_mov_b32_e32 v139, 1.0
	s_nop 0
	v_addc_co_u32_e32 v7, vcc, 0, v3, vcc
	global_load_dwordx4 v[110:113], v[4:5], off nt
	global_load_dwordx4 v[106:109], v[6:7], off nt
	v_add_co_u32_e32 v4, vcc, s92, v2
	s_nop 1
	v_addc_co_u32_e32 v5, vcc, 0, v3, vcc
	v_add_co_u32_e32 v6, vcc, s87, v2
	s_nop 1
	v_addc_co_u32_e32 v7, vcc, 0, v3, vcc
	global_load_dwordx4 v[102:105], v[4:5], off nt
	global_load_dwordx4 v[98:101], v[6:7], off nt
	v_add_co_u32_e32 v4, vcc, s93, v2
	s_nop 1
	v_addc_co_u32_e32 v5, vcc, 0, v3, vcc
	v_add_co_u32_e32 v6, vcc, s94, v2
	s_nop 1
	v_addc_co_u32_e32 v7, vcc, 0, v3, vcc
	global_load_dwordx4 v[94:97], v[4:5], off nt
	global_load_dwordx4 v[90:93], v[6:7], off nt
	v_add_co_u32_e32 v4, vcc, s95, v2
	s_nop 1
	v_addc_co_u32_e32 v5, vcc, 0, v3, vcc
	v_add_co_u32_e32 v6, vcc, s96, v2
	s_nop 1
	v_addc_co_u32_e32 v7, vcc, 0, v3, vcc
	global_load_dwordx4 v[86:89], v[4:5], off nt
	global_load_dwordx4 v[82:85], v[6:7], off nt
	v_add_co_u32_e32 v4, vcc, s97, v2
	s_nop 1
	v_addc_co_u32_e32 v5, vcc, 0, v3, vcc
	v_add_co_u32_e32 v6, vcc, s98, v2
	s_nop 1
	v_addc_co_u32_e32 v7, vcc, 0, v3, vcc
	global_load_dwordx4 v[78:81], v[4:5], off nt
	global_load_dwordx4 v[74:77], v[6:7], off nt
	v_add_co_u32_e32 v4, vcc, s99, v2
	s_nop 1
	v_addc_co_u32_e32 v5, vcc, 0, v3, vcc
	v_add_co_u32_e32 v6, vcc, s48, v2
	s_nop 1
	v_addc_co_u32_e32 v7, vcc, 0, v3, vcc
	global_load_dwordx4 v[70:73], v[4:5], off nt
	global_load_dwordx4 v[66:69], v[6:7], off nt
	v_add_co_u32_e32 v4, vcc, s49, v2
	s_nop 1
	v_addc_co_u32_e32 v5, vcc, 0, v3, vcc
	v_add_co_u32_e32 v6, vcc, s50, v2
	s_nop 1
	v_addc_co_u32_e32 v7, vcc, 0, v3, vcc
	global_load_dwordx4 v[62:65], v[4:5], off nt
	global_load_dwordx4 v[58:61], v[6:7], off nt
	v_add_co_u32_e32 v4, vcc, s51, v2
	s_nop 1
	v_addc_co_u32_e32 v5, vcc, 0, v3, vcc
	v_add_co_u32_e32 v6, vcc, s52, v2
	s_nop 1
	v_addc_co_u32_e32 v7, vcc, 0, v3, vcc
	global_load_dwordx4 v[54:57], v[4:5], off nt
	global_load_dwordx4 v[50:53], v[6:7], off nt
	v_add_co_u32_e32 v4, vcc, s53, v2
	s_nop 1
	v_addc_co_u32_e32 v5, vcc, 0, v3, vcc
	v_add_co_u32_e32 v6, vcc, s54, v2
	s_nop 1
	v_addc_co_u32_e32 v7, vcc, 0, v3, vcc
	global_load_dwordx4 v[46:49], v[4:5], off nt
	global_load_dwordx4 v[42:45], v[6:7], off nt
	v_add_co_u32_e32 v4, vcc, s55, v2
	s_nop 1
	v_addc_co_u32_e32 v5, vcc, 0, v3, vcc
	v_add_co_u32_e32 v6, vcc, s56, v2
	s_nop 1
	v_addc_co_u32_e32 v7, vcc, 0, v3, vcc
	global_load_dwordx4 v[38:41], v[4:5], off nt
	global_load_dwordx4 v[34:37], v[6:7], off nt
	v_add_co_u32_e32 v4, vcc, s57, v2
	s_nop 1
	v_addc_co_u32_e32 v5, vcc, 0, v3, vcc
	v_add_co_u32_e32 v6, vcc, s59, v2
	s_nop 1
	v_addc_co_u32_e32 v7, vcc, 0, v3, vcc
	global_load_dwordx4 v[30:33], v[4:5], off nt
	global_load_dwordx4 v[26:29], v[6:7], off nt
	v_add_co_u32_e32 v4, vcc, s60, v2
	s_nop 1
	v_addc_co_u32_e32 v5, vcc, 0, v3, vcc
	v_add_co_u32_e32 v6, vcc, s62, v2
	s_nop 1
	v_addc_co_u32_e32 v7, vcc, 0, v3, vcc
	global_load_dwordx4 v[22:25], v[4:5], off nt
	global_load_dwordx4 v[18:21], v[6:7], off nt
	v_add_co_u32_e32 v4, vcc, s63, v2
	s_nop 1
	v_addc_co_u32_e32 v5, vcc, 0, v3, vcc
	v_add_co_u32_e32 v6, vcc, 0x273000, v2
	s_nop 1
	v_addc_co_u32_e32 v7, vcc, 0, v3, vcc
	global_load_dwordx4 v[14:17], v[4:5], off nt
	global_load_dwordx4 v[10:13], v[6:7], off nt
	v_add_co_u32_e32 v4, vcc, 0x294000, v2
	s_nop 1
	v_addc_co_u32_e32 v5, vcc, 0, v3, vcc
	v_add_co_u32_e32 v2, vcc, 0x29f000, v2
	s_nop 1
	v_addc_co_u32_e32 v3, vcc, 0, v3, vcc
	global_load_dwordx4 v[6:9], v[4:5], off nt
	s_nop 0
	global_load_dwordx4 v[2:5], v[2:3], off nt
	s_andn2_b64 vcc, exec, s[34:35]
	s_cbranch_vccnz .LBB0_64
	v_lshlrev_b32_e32 v132, 2, v137
	global_load_dwordx2 v[138:139], v132, s[44:45]
	v_or_b32_e32 v228, s71, v166
	v_lshlrev_b32_e32 v228, 2, v228
	global_load_dwordx2 v[192:193], v228, s[44:45]
	v_or_b32_e32 v228, s71, v167
	v_lshlrev_b32_e32 v228, 2, v228
	global_load_dwordx2 v[194:195], v228, s[44:45]
	v_or_b32_e32 v228, s71, v169
	v_lshlrev_b32_e32 v228, 2, v228
	global_load_dwordx2 v[196:197], v228, s[44:45]
	v_or_b32_e32 v228, s71, v171
	v_lshlrev_b32_e32 v228, 2, v228
	global_load_dwordx2 v[198:199], v228, s[44:45]
	v_or_b32_e32 v228, s71, v173
	v_lshlrev_b32_e32 v228, 2, v228
	global_load_dwordx2 v[200:201], v228, s[44:45]
	v_or_b32_e32 v228, s71, v175
	v_lshlrev_b32_e32 v228, 2, v228
	global_load_dwordx2 v[202:203], v228, s[44:45]
	v_or_b32_e32 v228, s71, v177
	v_lshlrev_b32_e32 v228, 2, v228
	global_load_dwordx2 v[204:205], v228, s[44:45]
	v_or_b32_e32 v228, s71, v179
	v_lshlrev_b32_e32 v228, 2, v228
	global_load_dwordx2 v[206:207], v228, s[44:45]
	v_or_b32_e32 v228, s71, v181
	v_lshlrev_b32_e32 v228, 2, v228
	global_load_dwordx2 v[208:209], v228, s[44:45]
	v_or_b32_e32 v228, s71, v183
	v_lshlrev_b32_e32 v228, 2, v228
	global_load_dwordx2 v[210:211], v228, s[44:45]
	v_or_b32_e32 v228, s71, v185
	v_lshlrev_b32_e32 v228, 2, v228
	global_load_dwordx2 v[212:213], v228, s[44:45]
	v_or_b32_e32 v228, s71, v187
	v_lshlrev_b32_e32 v228, 2, v228
	global_load_dwordx2 v[214:215], v228, s[44:45]
	v_or_b32_e32 v228, s71, v188
	v_lshlrev_b32_e32 v228, 2, v228
	global_load_dwordx2 v[216:217], v228, s[44:45]
	v_or_b32_e32 v228, s71, v189
	v_lshlrev_b32_e32 v228, 2, v228
	global_load_dwordx2 v[218:219], v228, s[44:45]
	v_or_b32_e32 v228, s71, v190
	v_lshlrev_b32_e32 v228, 2, v228
	global_load_dwordx2 v[230:231], v228, s[44:45]

.LBB0_96:
	s_andn2_b64 vcc, exec, s[4:5]
	s_cbranch_vccnz .LBB0_13
	s_mul_i32 s4, s42, 0x5800000
	s_mul_hi_i32 s2, s42, 0x5800000
	s_add_u32 s4, s14, s4
	s_addc_u32 s5, s15, s2
	s_lshl_b32 s42, s42, 11
	s_ashr_i32 s43, s42, 31
	s_lshl_b64 s[42:43], s[42:43], 2
	s_add_u32 s42, s12, s42
	s_mul_i32 s2, s70, 0xba3
	s_addc_u32 s43, s13, s43
	s_lshr_b32 s38, s2, 31
	s_ashr_i32 s2, s2, 18
	s_add_i32 s38, s2, s38
	s_mul_i32 s2, s38, 0x58
	s_sub_i32 s2, s70, s2
	s_lshl_b32 s45, s38, 6
	s_sext_i32_i16 s44, s2
	s_bitcmp0_b32 s2, 0
	s_cselect_b32 s2, 0, 0x1600
	s_lshl_b32 s70, s44, 6
	s_and_b32 s70, s70, 0xffffff80
	v_or_b32_e32 v136, s45, v165
	s_add_i32 s70, s2, s70
	v_mul_hi_i32_i24_e32 v3, 0xb000, v136
	v_mul_i32_i24_e32 v2, 0xb000, v136
	v_lshl_add_u64 v[2:3], s[4:5], 0, v[2:3]
	s_ashr_i32 s71, s70, 31
	v_lshl_add_u64 v[2:3], s[70:71], 2, v[2:3]
	v_lshlrev_b32_e32 v132, 2, v130
	v_lshl_add_u64 v[2:3], v[2:3], 0, v[132:133]
	v_add_co_u32_e32 v4, vcc, s88, v2
	v_cndmask_b32_e64 v132, 0, 1, s[36:37]
	s_nop 0
	v_addc_co_u32_e32 v5, vcc, 0, v3, vcc
	global_load_dwordx4 v[126:129], v[2:3], off nt
	global_load_dwordx4 v[122:125], v[4:5], off nt
	v_add_co_u32_e32 v4, vcc, s89, v2
	v_mov_b32_e32 v138, 1.0
	s_nop 0
	v_addc_co_u32_e32 v5, vcc, 0, v3, vcc
	v_add_co_u32_e32 v6, vcc, s90, v2
	v_cmp_ne_u32_e64 s[4:5], 1, v132
	s_nop 0
	v_addc_co_u32_e32 v7, vcc, 0, v3, vcc
	global_load_dwordx4 v[118:121], v[4:5], off nt
	global_load_dwordx4 v[114:117], v[6:7], off nt
	v_add_co_u32_e32 v4, vcc, s76, v2
	v_mov_b32_e32 v140, 1.0
	s_nop 0
	v_addc_co_u32_e32 v5, vcc, 0, v3, vcc
	v_add_co_u32_e32 v6, vcc, s91, v2
	v_mov_b32_e32 v141, 1.0
	s_nop 0
	v_addc_co_u32_e32 v7, vcc, 0, v3, vcc
	global_load_dwordx4 v[110:113], v[4:5], off nt
	global_load_dwordx4 v[106:109], v[6:7], off nt
	v_add_co_u32_e32 v4, vcc, s92, v2
	s_nop 1
	v_addc_co_u32_e32 v5, vcc, 0, v3, vcc
	v_add_co_u32_e32 v6, vcc, s87, v2
	s_nop 1
	v_addc_co_u32_e32 v7, vcc, 0, v3, vcc
	global_load_dwordx4 v[102:105], v[4:5], off nt
	global_load_dwordx4 v[98:101], v[6:7], off nt
	v_add_co_u32_e32 v4, vcc, s93, v2
	s_nop 1
	v_addc_co_u32_e32 v5, vcc, 0, v3, vcc
	v_add_co_u32_e32 v6, vcc, s94, v2
	s_nop 1
	v_addc_co_u32_e32 v7, vcc, 0, v3, vcc
	global_load_dwordx4 v[94:97], v[4:5], off nt
	global_load_dwordx4 v[90:93], v[6:7], off nt
	v_add_co_u32_e32 v4, vcc, s95, v2
	s_nop 1
	v_addc_co_u32_e32 v5, vcc, 0, v3, vcc
	v_add_co_u32_e32 v6, vcc, s96, v2
	s_nop 1
	v_addc_co_u32_e32 v7, vcc, 0, v3, vcc
	global_load_dwordx4 v[86:89], v[4:5], off nt
	global_load_dwordx4 v[82:85], v[6:7], off nt
	v_add_co_u32_e32 v4, vcc, s97, v2
	s_nop 1
	v_addc_co_u32_e32 v5, vcc, 0, v3, vcc
	v_add_co_u32_e32 v6, vcc, s98, v2
	s_nop 1
	v_addc_co_u32_e32 v7, vcc, 0, v3, vcc
	global_load_dwordx4 v[78:81], v[4:5], off nt
	global_load_dwordx4 v[74:77], v[6:7], off nt
	v_add_co_u32_e32 v4, vcc, s99, v2
	s_nop 1
	v_addc_co_u32_e32 v5, vcc, 0, v3, vcc
	v_add_co_u32_e32 v6, vcc, s48, v2
	s_nop 1
	v_addc_co_u32_e32 v7, vcc, 0, v3, vcc
	global_load_dwordx4 v[70:73], v[4:5], off nt
	global_load_dwordx4 v[66:69], v[6:7], off nt
	v_add_co_u32_e32 v4, vcc, s49, v2
	s_nop 1
	v_addc_co_u32_e32 v5, vcc, 0, v3, vcc
	v_add_co_u32_e32 v6, vcc, s50, v2
	s_nop 1
	v_addc_co_u32_e32 v7, vcc, 0, v3, vcc
	global_load_dwordx4 v[62:65], v[4:5], off nt
	global_load_dwordx4 v[58:61], v[6:7], off nt
	v_add_co_u32_e32 v4, vcc, s51, v2
	s_nop 1
	v_addc_co_u32_e32 v5, vcc, 0, v3, vcc
	v_add_co_u32_e32 v6, vcc, s52, v2
	s_nop 1
	v_addc_co_u32_e32 v7, vcc, 0, v3, vcc
	global_load_dwordx4 v[54:57], v[4:5], off nt
	global_load_dwordx4 v[50:53], v[6:7], off nt
	v_add_co_u32_e32 v4, vcc, s53, v2
	s_nop 1
	v_addc_co_u32_e32 v5, vcc, 0, v3, vcc
	v_add_co_u32_e32 v6, vcc, s54, v2
	s_nop 1
	v_addc_co_u32_e32 v7, vcc, 0, v3, vcc
	global_load_dwordx4 v[46:49], v[4:5], off nt
	global_load_dwordx4 v[42:45], v[6:7], off nt
	v_add_co_u32_e32 v4, vcc, s55, v2
	s_nop 1
	v_addc_co_u32_e32 v5, vcc, 0, v3, vcc
	v_add_co_u32_e32 v6, vcc, s56, v2
	s_nop 1
	v_addc_co_u32_e32 v7, vcc, 0, v3, vcc
	global_load_dwordx4 v[38:41], v[4:5], off nt
	global_load_dwordx4 v[34:37], v[6:7], off nt
	v_add_co_u32_e32 v4, vcc, s57, v2
	s_nop 1
	v_addc_co_u32_e32 v5, vcc, 0, v3, vcc
	v_add_co_u32_e32 v6, vcc, s59, v2
	s_nop 1
	v_addc_co_u32_e32 v7, vcc, 0, v3, vcc
	global_load_dwordx4 v[30:33], v[4:5], off nt
	global_load_dwordx4 v[26:29], v[6:7], off nt
	v_add_co_u32_e32 v4, vcc, s60, v2
	s_nop 1
	v_addc_co_u32_e32 v5, vcc, 0, v3, vcc
	v_add_co_u32_e32 v6, vcc, s62, v2
	s_nop 1
	v_addc_co_u32_e32 v7, vcc, 0, v3, vcc
	global_load_dwordx4 v[22:25], v[4:5], off nt
	global_load_dwordx4 v[18:21], v[6:7], off nt
	v_add_co_u32_e32 v4, vcc, s63, v2
	s_nop 1
	v_addc_co_u32_e32 v5, vcc, 0, v3, vcc
	v_add_co_u32_e32 v6, vcc, 0x273000, v2
	s_nop 1
	v_addc_co_u32_e32 v7, vcc, 0, v3, vcc
	global_load_dwordx4 v[14:17], v[4:5], off nt
	global_load_dwordx4 v[10:13], v[6:7], off nt
	v_add_co_u32_e32 v4, vcc, 0x294000, v2
	s_nop 1
	v_addc_co_u32_e32 v5, vcc, 0, v3, vcc
	v_add_co_u32_e32 v2, vcc, 0x29f000, v2
	s_nop 1
	v_addc_co_u32_e32 v3, vcc, 0, v3, vcc
	global_load_dwordx4 v[6:9], v[4:5], off nt
	s_nop 0
	global_load_dwordx4 v[2:5], v[2:3], off nt
	s_andn2_b64 vcc, exec, s[36:37]
	s_cbranch_vccnz .LBB0_99
	v_ashrrev_i32_e32 v137, 31, v136
	v_lshl_add_u64 v[136:137], v[136:137], 2, s[42:43]
	global_load_dwordx2 v[140:141], v[136:137], off
	v_or_b32_e32 v228, s45, v166
	v_ashrrev_i32_e32 v229, 31, v228
	v_lshl_add_u64 v[228:229], v[228:229], 2, s[42:43]
	global_load_dwordx2 v[192:193], v[228:229], off
	v_or_b32_e32 v228, s45, v167
	v_ashrrev_i32_e32 v229, 31, v228
	v_lshl_add_u64 v[228:229], v[228:229], 2, s[42:43]
	global_load_dwordx2 v[194:195], v[228:229], off
	v_or_b32_e32 v228, s45, v169
	v_ashrrev_i32_e32 v229, 31, v228
	v_lshl_add_u64 v[228:229], v[228:229], 2, s[42:43]
	global_load_dwordx2 v[196:197], v[228:229], off
	v_or_b32_e32 v228, s45, v171
	v_ashrrev_i32_e32 v229, 31, v228
	v_lshl_add_u64 v[228:229], v[228:229], 2, s[42:43]
	global_load_dwordx2 v[198:199], v[228:229], off
	v_or_b32_e32 v228, s45, v173
	v_ashrrev_i32_e32 v229, 31, v228
	v_lshl_add_u64 v[228:229], v[228:229], 2, s[42:43]
	global_load_dwordx2 v[200:201], v[228:229], off
	v_or_b32_e32 v228, s45, v175
	v_ashrrev_i32_e32 v229, 31, v228
	v_lshl_add_u64 v[228:229], v[228:229], 2, s[42:43]
	global_load_dwordx2 v[202:203], v[228:229], off
	v_or_b32_e32 v228, s45, v177
	v_ashrrev_i32_e32 v229, 31, v228
	v_lshl_add_u64 v[228:229], v[228:229], 2, s[42:43]
	global_load_dwordx2 v[204:205], v[228:229], off
	v_or_b32_e32 v228, s45, v179
	v_ashrrev_i32_e32 v229, 31, v228
	v_lshl_add_u64 v[228:229], v[228:229], 2, s[42:43]
	global_load_dwordx2 v[206:207], v[228:229], off
	v_or_b32_e32 v228, s45, v181
	v_ashrrev_i32_e32 v229, 31, v228
	v_lshl_add_u64 v[228:229], v[228:229], 2, s[42:43]
	global_load_dwordx2 v[208:209], v[228:229], off
	v_or_b32_e32 v228, s45, v183
	v_ashrrev_i32_e32 v229, 31, v228
	v_lshl_add_u64 v[228:229], v[228:229], 2, s[42:43]
	global_load_dwordx2 v[210:211], v[228:229], off
	v_or_b32_e32 v228, s45, v185
	v_ashrrev_i32_e32 v229, 31, v228
	v_lshl_add_u64 v[228:229], v[228:229], 2, s[42:43]
	global_load_dwordx2 v[212:213], v[228:229], off
	v_or_b32_e32 v228, s45, v187
	v_ashrrev_i32_e32 v229, 31, v228
	v_lshl_add_u64 v[228:229], v[228:229], 2, s[42:43]
	global_load_dwordx2 v[214:215], v[228:229], off
	v_or_b32_e32 v228, s45, v188
	v_ashrrev_i32_e32 v229, 31, v228
	v_lshl_add_u64 v[228:229], v[228:229], 2, s[42:43]
	global_load_dwordx2 v[216:217], v[228:229], off
	v_or_b32_e32 v228, s45, v189
	v_ashrrev_i32_e32 v229, 31, v228
	v_lshl_add_u64 v[228:229], v[228:229], 2, s[42:43]
	global_load_dwordx2 v[218:219], v[228:229], off
	v_or_b32_e32 v228, s45, v190
	v_ashrrev_i32_e32 v229, 31, v228
	v_lshl_add_u64 v[228:229], v[228:229], 2, s[42:43]
	global_load_dwordx2 v[230:231], v[228:229], off

.LBB0_133:
	v_lshl_add_u64 v[12:13], s[64:65], 0, v[6:7]
	v_add_co_u32_e64 v40, s[6:7], s2, v12
	global_load_dwordx4 v[8:11], v[4:5], off offset:-4096 nt
	global_load_dwordx4 v[192:195], v[4:5], off offset:-3072 nt
	global_load_dwordx4 v[196:199], v[4:5], off offset:-2048 nt
	global_load_dwordx4 v[200:203], v[4:5], off offset:-1024 nt
	global_load_dwordx4 v[204:207], v[4:5], off nt
	global_load_dwordx4 v[208:211], v[4:5], off offset:1024 nt
	global_load_dwordx4 v[212:215], v[4:5], off offset:2048 nt
	global_load_dwordx4 v[216:219], v[4:5], off offset:3072 nt
	s_nop 0
	v_addc_co_u32_e64 v41, s[6:7], 0, v13, s[6:7]
	s_waitcnt vmcnt(7)
	v_cvt_pk_bf16_f32 v12, v8, v9
	v_cvt_pk_bf16_f32 v13, v10, v11
	global_store_dwordx2 v[40:41], v[12:13], off
	s_waitcnt vmcnt(7)
	v_mov_b32_e32 v12, v192
	v_mov_b32_e32 v13, v193
	v_mov_b32_e32 v14, v194
	v_mov_b32_e32 v15, v195
	v_cvt_pk_bf16_f32 v16, v12, v13
	v_cvt_pk_bf16_f32 v17, v14, v15
	global_store_dwordx2 v[40:41], v[16:17], off offset:512
	s_waitcnt vmcnt(7)
	v_mov_b32_e32 v16, v196
	v_mov_b32_e32 v17, v197
	v_mov_b32_e32 v18, v198
	v_mov_b32_e32 v19, v199
	v_cvt_pk_bf16_f32 v20, v16, v17
	v_cvt_pk_bf16_f32 v21, v18, v19
	global_store_dwordx2 v[40:41], v[20:21], off offset:1024
	s_waitcnt vmcnt(7)
	v_mov_b32_e32 v20, v200
	v_mov_b32_e32 v21, v201
	v_mov_b32_e32 v22, v202
	v_mov_b32_e32 v23, v203
	v_cvt_pk_bf16_f32 v24, v20, v21
	v_cvt_pk_bf16_f32 v25, v22, v23
	global_store_dwordx2 v[40:41], v[24:25], off offset:1536
	s_waitcnt vmcnt(7)
	v_mov_b32_e32 v24, v204
	v_mov_b32_e32 v25, v205
	v_mov_b32_e32 v26, v206
	v_mov_b32_e32 v27, v207
	v_cvt_pk_bf16_f32 v28, v24, v25
	v_cvt_pk_bf16_f32 v29, v26, v27
	global_store_dwordx2 v[40:41], v[28:29], off offset:2048
	s_waitcnt vmcnt(7)
	v_mov_b32_e32 v28, v208
	v_mov_b32_e32 v29, v209
	v_mov_b32_e32 v30, v210
	v_mov_b32_e32 v31, v211
	v_cvt_pk_bf16_f32 v32, v28, v29
	v_cvt_pk_bf16_f32 v33, v30, v31
	global_store_dwordx2 v[40:41], v[32:33], off offset:2560
	s_waitcnt vmcnt(7)
	v_mov_b32_e32 v32, v212
	v_mov_b32_e32 v33, v213
	v_mov_b32_e32 v34, v214
	v_mov_b32_e32 v35, v215
	v_cvt_pk_bf16_f32 v36, v32, v33
	v_cvt_pk_bf16_f32 v37, v34, v35
	global_store_dwordx2 v[40:41], v[36:37], off offset:3072
	v_mov_b32_e32 v42, 0
	v_mul_f32_e32 v9, v9, v9
	v_mul_f32_e32 v11, v11, v11
	v_fmac_f32_e32 v9, v8, v8
	v_fmac_f32_e32 v11, v10, v10
	v_add_f32_e32 v8, v9, v11
	v_mul_f32_e32 v9, v13, v13
	v_mul_f32_e32 v10, v15, v15
	v_fmac_f32_e32 v9, v12, v12
	v_fmac_f32_e32 v10, v14, v14
	v_add_f32_e32 v9, v9, v10
	v_add_f32_e32 v8, v8, v9
	v_mul_f32_e32 v9, v17, v17
	v_mul_f32_e32 v10, v19, v19
	v_fmac_f32_e32 v9, v16, v16
	v_fmac_f32_e32 v10, v18, v18
	v_add_f32_e32 v9, v9, v10
	v_add_f32_e32 v8, v8, v9
	v_mul_f32_e32 v9, v21, v21
	v_mul_f32_e32 v10, v23, v23
	v_fmac_f32_e32 v9, v20, v20
	v_fmac_f32_e32 v10, v22, v22
	v_add_f32_e32 v9, v9, v10
	v_add_f32_e32 v8, v8, v9
	v_mul_f32_e32 v9, v25, v25
	v_mul_f32_e32 v10, v27, v27
	v_fmac_f32_e32 v9, v24, v24
	v_fmac_f32_e32 v10, v26, v26
	v_add_f32_e32 v9, v9, v10
	v_add_f32_e32 v8, v8, v9
	v_mul_f32_e32 v9, v29, v29
	v_mul_f32_e32 v10, v31, v31
	v_fmac_f32_e32 v9, v28, v28
	v_fmac_f32_e32 v10, v30, v30
	v_add_f32_e32 v9, v9, v10
	v_add_f32_e32 v8, v8, v9
	v_mul_f32_e32 v9, v33, v33
	v_mul_f32_e32 v10, v35, v35
	v_fmac_f32_e32 v9, v32, v32
	v_fmac_f32_e32 v10, v34, v34
	v_add_f32_e32 v9, v9, v10
	s_waitcnt vmcnt(7)
	v_mov_b32_e32 v36, v216
	v_mov_b32_e32 v37, v217
	v_mov_b32_e32 v38, v218
	v_mov_b32_e32 v39, v219
	v_mul_f32_e32 v11, v37, v37
	v_mul_f32_e32 v12, v39, v39
	v_add_f32_e32 v10, v8, v9
	v_cvt_pk_bf16_f32 v8, v36, v37
	v_fmac_f32_e32 v11, v36, v36
	v_fmac_f32_e32 v12, v38, v38
	v_cvt_pk_bf16_f32 v9, v38, v39
	global_store_dwordx2 v[40:41], v[8:9], off offset:3584
	v_add_f32_e32 v8, v11, v12
	v_add_f32_e32 v8, v10, v8
	v_mov_b32_e32 v9, 0
	s_nop 0
	v_add_f32_dpp v8, v8, v8 row_shr:1 row_mask:0xf bank_mask:0xf bound_ctrl:1
	s_nop 1
	v_add_f32_dpp v8, v8, v8 row_shr:2 row_mask:0xf bank_mask:0xf bound_ctrl:1
	s_nop 1
	v_add_f32_dpp v8, v8, v8 row_shr:4 row_mask:0xf bank_mask:0xf bound_ctrl:1
	s_nop 1
	v_add_f32_dpp v8, v8, v8 row_shr:8 row_mask:0xf bank_mask:0xf bound_ctrl:1
	s_nop 1
	v_mov_b32_dpp v42, v8 row_bcast:15 row_mask:0xa bank_mask:0xf
	v_add_f32_e32 v8, v8, v42
	s_nop 1
	v_mov_b32_dpp v9, v8 row_bcast:31 row_mask:0xc bank_mask:0xf
	v_add_f32_e32 v8, v8, v9
	s_nop 0
	v_readlane_b32 s14, v8, 63
	s_and_saveexec_b64 s[6:7], s[4:5]
	s_cbranch_execz .LBB0_132
	v_mov_b32_e32 v8, s14
	v_cndmask_b32_e32 v10, 0, v8, vcc
	v_lshl_add_u64 v[8:9], s[64:65], 0, v[2:3]
	global_store_dword v[8:9], v10, off
	s_branch .LBB0_132
